# scan LDS reads as conflict-free ds_read_b64 pairs; P7 down-proj: balanced K-range schedule (every workgroup ~50 K-pairs, 2 partials per tile) instead of 3 rounds of half-K units
# speedup vs baseline: 1.0466x; 1.0466x over previous
.LBB0_747:
	s_or_b64 exec, exec, s[36:37]
	v_lshl_add_u64 v[16:17], s[30:31], 0, v[152:153]
	s_mov_b64 s[34:35], 0xe1800
	v_lshl_add_u64 v[18:19], v[16:17], 0, s[34:35]
	v_add_co_u32_e32 v16, vcc, 0xe1000, v16
	v_cvt_pk_bf16_f32 v116, v52, v53
	s_nop 0
	v_addc_co_u32_e32 v17, vcc, 0, v17, vcc
	global_load_dwordx4 v[24:27], v[16:17], off offset:2048
	s_nop 0
	global_load_dwordx4 v[16:19], v[18:19], off offset:16
	v_mov_b32_e32 v204, s24
	ds_read_b32 v174, v204
	ds_read_b64 v[244:245], v187 offset:0
	ds_read_b64 v[246:247], v187 offset:32
	ds_read_b64 v[248:249], v187 offset:17408
	ds_read_b64 v[250:251], v187 offset:17440
	ds_read_b64 v[252:253], v187 offset:64
	ds_read_b64 v[254:255], v187 offset:96
	ds_read_b64 v[200:201], v187 offset:17472
	ds_read_b64 v[202:203], v187 offset:17504
	v_cvt_pk_bf16_f32 v116, v52, v53
	v_cvt_pk_bf16_f32 v117, v54, v55
	v_cvt_pk_bf16_f32 v118, v48, v49
	v_cvt_pk_bf16_f32 v119, v50, v51
	v_cvt_pk_bf16_f32 v112, v44, v45
	v_cvt_pk_bf16_f32 v113, v46, v47
	v_cvt_pk_bf16_f32 v114, v20, v21
	v_cvt_pk_bf16_f32 v115, v22, v23
	v_cvt_pk_bf16_f32 v108, v40, v41
	v_cvt_pk_bf16_f32 v109, v42, v43
	v_cvt_pk_bf16_f32 v110, v36, v37
	v_cvt_pk_bf16_f32 v111, v38, v39
	v_cvt_pk_bf16_f32 v104, v32, v33
	v_cvt_pk_bf16_f32 v105, v34, v35
	v_cvt_pk_bf16_f32 v106, v28, v29
	v_cvt_pk_bf16_f32 v107, v30, v31
	s_mov_b64 s[34:35], 0xe0000
	v_lshl_add_u64 v[152:153], v[152:153], 0, s[34:35]
	v_lshl_add_u64 v[154:155], v[154:155], 0, s[26:27]
	v_lshl_add_u64 v[156:157], v[156:157], 0, s[26:27]
	v_lshl_add_u64 v[158:159], v[158:159], 0, s[26:27]
	v_lshl_add_u64 v[160:161], v[160:161], 0, s[26:27]
	v_lshl_add_u64 v[162:163], v[162:163], 0, s[26:27]
	v_lshl_add_u64 v[164:165], v[164:165], 0, s[26:27]
	v_lshl_add_u64 v[166:167], v[166:167], 0, s[26:27]
	v_lshl_add_u64 v[168:169], v[168:169], 0, s[26:27]
	v_lshl_add_u64 v[170:171], v[170:171], 0, s[26:27]
	v_lshl_add_u64 v[172:173], v[172:173], 0, s[26:27]
	s_waitcnt lgkmcnt(6)
	v_mfma_f32_16x16x32_bf16 v[120:123], v[244:247], v[116:119], 0
	ds_read_b64 v[244:245], v187 offset:128
	ds_read_b64 v[246:247], v187 offset:160
	s_waitcnt lgkmcnt(6)
	v_mfma_f32_16x16x32_bf16 v[136:139], v[248:251], v[116:119], 0
	ds_read_b64 v[248:249], v187 offset:17536
	ds_read_b64 v[250:251], v187 offset:17568
	s_waitcnt lgkmcnt(6)
	v_mfma_f32_16x16x32_bf16 v[120:123], v[252:255], v[112:115], v[120:123]
	ds_read_b64 v[252:253], v187 offset:192
	ds_read_b64 v[254:255], v187 offset:224
	v_pk_mul_f32 v[52:53], v[52:53], v[174:175] op_sel_hi:[1,0]
	v_pk_mul_f32 v[54:55], v[54:55], v[174:175] op_sel_hi:[1,0]
	s_waitcnt lgkmcnt(6)
	v_mfma_f32_16x16x32_bf16 v[136:139], v[200:203], v[112:115], v[136:139]
	ds_read_b64 v[200:201], v187 offset:17600
	ds_read_b64 v[202:203], v187 offset:17632
	v_pk_mul_f32 v[48:49], v[48:49], v[174:175] op_sel_hi:[1,0]
	s_waitcnt lgkmcnt(6)
	v_mfma_f32_16x16x32_bf16 v[120:123], v[244:247], v[108:111], v[120:123]
	ds_read_b64 v[244:245], v187 offset:4352
	ds_read_b64 v[246:247], v187 offset:4384
	v_pk_mul_f32 v[50:51], v[50:51], v[174:175] op_sel_hi:[1,0]
	v_pk_mul_f32 v[44:45], v[44:45], v[174:175] op_sel_hi:[1,0]
	s_waitcnt lgkmcnt(6)
	v_mfma_f32_16x16x32_bf16 v[136:139], v[248:251], v[108:111], v[136:139]
	ds_read_b64 v[248:249], v187 offset:21760
	ds_read_b64 v[250:251], v187 offset:21792
	v_pk_mul_f32 v[46:47], v[46:47], v[174:175] op_sel_hi:[1,0]
	s_waitcnt lgkmcnt(6)
	v_mfma_f32_16x16x32_bf16 v[120:123], v[252:255], v[104:107], v[120:123]
	ds_read_b64 v[252:253], v187 offset:4416
	ds_read_b64 v[254:255], v187 offset:4448
	v_pk_mul_f32 v[20:21], v[20:21], v[174:175] op_sel_hi:[1,0]
	v_pk_mul_f32 v[22:23], v[22:23], v[174:175] op_sel_hi:[1,0]
	s_waitcnt lgkmcnt(6)
	v_mfma_f32_16x16x32_bf16 v[136:139], v[200:203], v[104:107], v[136:139]
	ds_read_b64 v[200:201], v187 offset:21824
	ds_read_b64 v[202:203], v187 offset:21856
	v_pk_mul_f32 v[40:41], v[40:41], v[174:175] op_sel_hi:[1,0]
	s_waitcnt lgkmcnt(6)
	v_mfma_f32_16x16x32_bf16 v[124:127], v[244:247], v[116:119], 0
	ds_read_b64 v[244:245], v187 offset:4480
	ds_read_b64 v[246:247], v187 offset:4512
	v_pk_mul_f32 v[42:43], v[42:43], v[174:175] op_sel_hi:[1,0]
	v_pk_mul_f32 v[36:37], v[36:37], v[174:175] op_sel_hi:[1,0]
	s_waitcnt lgkmcnt(6)
	v_mfma_f32_16x16x32_bf16 v[140:143], v[248:251], v[116:119], 0
	ds_read_b64 v[248:249], v187 offset:21888
	ds_read_b64 v[250:251], v187 offset:21920
	v_pk_mul_f32 v[38:39], v[38:39], v[174:175] op_sel_hi:[1,0]
	s_waitcnt lgkmcnt(6)
	v_mfma_f32_16x16x32_bf16 v[124:127], v[252:255], v[112:115], v[124:127]
	ds_read_b64 v[252:253], v187 offset:4544
	ds_read_b64 v[254:255], v187 offset:4576
	v_pk_mul_f32 v[32:33], v[32:33], v[174:175] op_sel_hi:[1,0]
	v_pk_mul_f32 v[34:35], v[34:35], v[174:175] op_sel_hi:[1,0]
	s_waitcnt lgkmcnt(6)
	v_mfma_f32_16x16x32_bf16 v[140:143], v[200:203], v[112:115], v[140:143]
	ds_read_b64 v[200:201], v187 offset:21952
	ds_read_b64 v[202:203], v187 offset:21984
	v_pk_mul_f32 v[28:29], v[28:29], v[174:175] op_sel_hi:[1,0]
	s_waitcnt lgkmcnt(6)
	v_mfma_f32_16x16x32_bf16 v[124:127], v[244:247], v[108:111], v[124:127]
	ds_read_b64 v[244:245], v187 offset:8704
	ds_read_b64 v[246:247], v187 offset:8736
	v_pk_mul_f32 v[30:31], v[30:31], v[174:175] op_sel_hi:[1,0]
	s_waitcnt lgkmcnt(6)
	v_mfma_f32_16x16x32_bf16 v[140:143], v[248:251], v[108:111], v[140:143]
	ds_read_b64 v[248:249], v187 offset:26112
	ds_read_b64 v[250:251], v187 offset:26144
	s_waitcnt lgkmcnt(6)
	v_mfma_f32_16x16x32_bf16 v[124:127], v[252:255], v[104:107], v[124:127]
	ds_read_b64 v[252:253], v187 offset:8768
	ds_read_b64 v[254:255], v187 offset:8800
	s_waitcnt lgkmcnt(6)
	v_mfma_f32_16x16x32_bf16 v[140:143], v[200:203], v[104:107], v[140:143]
	ds_read_b64 v[200:201], v187 offset:26176
	ds_read_b64 v[202:203], v187 offset:26208
	s_waitcnt lgkmcnt(6)
	v_mfma_f32_16x16x32_bf16 v[128:131], v[244:247], v[116:119], 0
	ds_read_b64 v[244:245], v187 offset:8832
	ds_read_b64 v[246:247], v187 offset:8864
	s_waitcnt lgkmcnt(6)
	v_mfma_f32_16x16x32_bf16 v[144:147], v[248:251], v[116:119], 0
	ds_read_b64 v[248:249], v187 offset:26240
	ds_read_b64 v[250:251], v187 offset:26272
	s_waitcnt lgkmcnt(6)
	v_mfma_f32_16x16x32_bf16 v[128:131], v[252:255], v[112:115], v[128:131]
	ds_read_b64 v[252:253], v187 offset:8896
	ds_read_b64 v[254:255], v187 offset:8928
	s_waitcnt lgkmcnt(6)
	v_mfma_f32_16x16x32_bf16 v[144:147], v[200:203], v[112:115], v[144:147]
	ds_read_b64 v[200:201], v187 offset:26304
	ds_read_b64 v[202:203], v187 offset:26336
	s_waitcnt lgkmcnt(6)
	v_mfma_f32_16x16x32_bf16 v[128:131], v[244:247], v[108:111], v[128:131]
	ds_read_b64 v[244:245], v187 offset:13056
	ds_read_b64 v[246:247], v187 offset:13088
	s_waitcnt lgkmcnt(6)
	v_mfma_f32_16x16x32_bf16 v[144:147], v[248:251], v[108:111], v[144:147]
	ds_read_b64 v[248:249], v187 offset:30464
	ds_read_b64 v[250:251], v187 offset:30496
	s_waitcnt lgkmcnt(6)
	v_mfma_f32_16x16x32_bf16 v[128:131], v[252:255], v[104:107], v[128:131]
	ds_read_b64 v[252:253], v187 offset:13120
	ds_read_b64 v[254:255], v187 offset:13152
	s_waitcnt lgkmcnt(6)
	v_mfma_f32_16x16x32_bf16 v[144:147], v[200:203], v[104:107], v[144:147]
	ds_read_b64 v[200:201], v187 offset:30528
	ds_read_b64 v[202:203], v187 offset:30560
	s_waitcnt lgkmcnt(6)
	v_mfma_f32_16x16x32_bf16 v[132:135], v[244:247], v[116:119], 0
	ds_read_b64 v[244:245], v187 offset:13184
	ds_read_b64 v[246:247], v187 offset:13216
	s_waitcnt lgkmcnt(6)
	v_mfma_f32_16x16x32_bf16 v[240:243], v[248:251], v[116:119], 0
	ds_read_b64 v[248:249], v187 offset:30592
	ds_read_b64 v[250:251], v187 offset:30624
	s_waitcnt lgkmcnt(6)
	v_mfma_f32_16x16x32_bf16 v[132:135], v[252:255], v[112:115], v[132:135]
	ds_read_b64 v[252:253], v187 offset:13248
	ds_read_b64 v[254:255], v187 offset:13280
	s_waitcnt lgkmcnt(6)
	v_mfma_f32_16x16x32_bf16 v[240:243], v[200:203], v[112:115], v[240:243]
	ds_read_b64 v[200:201], v187 offset:30656
	ds_read_b64 v[202:203], v187 offset:30688
	s_waitcnt lgkmcnt(6)
	v_mfma_f32_16x16x32_bf16 v[132:135], v[244:247], v[108:111], v[132:135]
	ds_read_b64 v[244:245], v186 offset:62464
	ds_read_b64 v[246:247], v186 offset:62496
	s_waitcnt lgkmcnt(6)
	v_mfma_f32_16x16x32_bf16 v[240:243], v[248:251], v[108:111], v[240:243]
	ds_read_b64 v[248:249], v186 offset:62528
	ds_read_b64 v[250:251], v186 offset:62560
	s_waitcnt lgkmcnt(6)
	v_mfma_f32_16x16x32_bf16 v[132:135], v[252:255], v[104:107], v[132:135]
	ds_read_b64 v[252:253], v185 offset:34816
	ds_read_b64 v[254:255], v185 offset:34848
	s_waitcnt lgkmcnt(6)
	v_mfma_f32_16x16x32_bf16 v[240:243], v[200:203], v[104:107], v[240:243]
	ds_read_b64 v[200:201], v185 offset:34880
	ds_read_b64 v[202:203], v185 offset:34912
	s_waitcnt lgkmcnt(6)
	v_lshlrev_b32_e32 v104, 16, v244
	v_and_b32_e32 v105, 0xffff0000, v244
	v_lshlrev_b32_e32 v106, 16, v245
	v_and_b32_e32 v107, 0xffff0000, v245
	v_pk_add_f32 v[120:121], v[104:105], v[120:121] neg_lo:[0,1] neg_hi:[0,1]
	v_pk_add_f32 v[122:123], v[106:107], v[122:123] neg_lo:[0,1] neg_hi:[0,1]
	v_lshlrev_b32_e32 v108, 16, v246
	v_and_b32_e32 v109, 0xffff0000, v246
	v_lshlrev_b32_e32 v110, 16, v247
	v_and_b32_e32 v111, 0xffff0000, v247
	v_pk_add_f32 v[124:125], v[108:109], v[124:125] neg_lo:[0,1] neg_hi:[0,1]
	v_pk_add_f32 v[126:127], v[110:111], v[126:127] neg_lo:[0,1] neg_hi:[0,1]
	ds_read_b64 v[244:245], v185 offset:37120
	ds_read_b64 v[246:247], v185 offset:37152
	v_cvt_pk_bf16_f32 v116, v120, v121
	v_cvt_pk_bf16_f32 v117, v122, v123
	v_cvt_pk_bf16_f32 v118, v124, v125
	v_cvt_pk_bf16_f32 v119, v126, v127
	s_waitcnt lgkmcnt(6)
	v_lshlrev_b32_e32 v104, 16, v248
	v_and_b32_e32 v105, 0xffff0000, v248
	v_lshlrev_b32_e32 v106, 16, v249
	v_and_b32_e32 v107, 0xffff0000, v249
	v_pk_add_f32 v[128:129], v[104:105], v[128:129] neg_lo:[0,1] neg_hi:[0,1]
	v_pk_add_f32 v[130:131], v[106:107], v[130:131] neg_lo:[0,1] neg_hi:[0,1]
	v_lshlrev_b32_e32 v108, 16, v250
	v_and_b32_e32 v109, 0xffff0000, v250
	v_lshlrev_b32_e32 v110, 16, v251
	v_and_b32_e32 v111, 0xffff0000, v251
	v_pk_add_f32 v[132:133], v[108:109], v[132:133] neg_lo:[0,1] neg_hi:[0,1]
	v_pk_add_f32 v[134:135], v[110:111], v[134:135] neg_lo:[0,1] neg_hi:[0,1]
	ds_read_b64 v[248:249], v185 offset:37184
	ds_read_b64 v[250:251], v185 offset:37216
	v_cvt_pk_bf16_f32 v112, v128, v129
	v_cvt_pk_bf16_f32 v113, v130, v131
	v_cvt_pk_bf16_f32 v114, v132, v133
	v_cvt_pk_bf16_f32 v115, v134, v135
	s_waitcnt lgkmcnt(6)
	s_nop 1
	v_mfma_f32_16x16x32_bf16 v[136:139], v[252:255], v[116:119], v[136:139]
	ds_read_b64 v[252:253], v185 offset:39424
	ds_read_b64 v[254:255], v185 offset:39456
	s_waitcnt lgkmcnt(6)
	v_mfma_f32_16x16x32_bf16 v[136:139], v[200:203], v[112:115], v[136:139]
	ds_read_b64 v[200:201], v185 offset:39488
	ds_read_b64 v[202:203], v185 offset:39520
	s_waitcnt lgkmcnt(6)
	v_mfma_f32_16x16x32_bf16 v[140:143], v[244:247], v[116:119], v[140:143]
	ds_read_b64 v[244:245], v185 offset:41728
	ds_read_b64 v[246:247], v185 offset:41760
	s_waitcnt lgkmcnt(6)
	v_mfma_f32_16x16x32_bf16 v[140:143], v[248:251], v[112:115], v[140:143]
	ds_read_b64 v[248:249], v185 offset:41792
	ds_read_b64 v[250:251], v185 offset:41824
	s_waitcnt lgkmcnt(6)
	v_mfma_f32_16x16x32_bf16 v[144:147], v[252:255], v[116:119], v[144:147]
	ds_read_b64 v[252:253], v185 offset:44032
	ds_read_b64 v[254:255], v185 offset:44064
	s_waitcnt lgkmcnt(6)
	v_mfma_f32_16x16x32_bf16 v[144:147], v[200:203], v[112:115], v[144:147]
	ds_read_b64 v[200:201], v185 offset:44096
	ds_read_b64 v[202:203], v185 offset:44128
	s_waitcnt lgkmcnt(6)
	v_mfma_f32_16x16x32_bf16 v[240:243], v[244:247], v[116:119], v[240:243]
	ds_read_b64 v[244:245], v185 offset:46336
	ds_read_b64 v[246:247], v185 offset:46368
	s_waitcnt lgkmcnt(6)
	v_mfma_f32_16x16x32_bf16 v[240:243], v[248:251], v[112:115], v[240:243]
	ds_read_b64 v[248:249], v185 offset:46400
	ds_read_b64 v[250:251], v185 offset:46432
	s_waitcnt lgkmcnt(6)
	v_mfma_f32_16x16x32_bf16 v[52:55], v[252:255], v[116:119], v[52:55]
	ds_read_b64 v[252:253], v185 offset:48640
	ds_read_b64 v[254:255], v185 offset:48672
	s_waitcnt lgkmcnt(6)
	v_mfma_f32_16x16x32_bf16 v[52:55], v[200:203], v[112:115], v[52:55]
	ds_read_b64 v[200:201], v185 offset:48704
	ds_read_b64 v[202:203], v185 offset:48736
	s_waitcnt lgkmcnt(6)
	v_mfma_f32_16x16x32_bf16 v[48:51], v[244:247], v[116:119], v[48:51]
	ds_read_b64 v[244:245], v185 offset:50944
	ds_read_b64 v[246:247], v185 offset:50976
	s_waitcnt lgkmcnt(6)
	v_mfma_f32_16x16x32_bf16 v[48:51], v[248:251], v[112:115], v[48:51]
	ds_read_b64 v[248:249], v185 offset:51008
	ds_read_b64 v[250:251], v185 offset:51040
	s_waitcnt lgkmcnt(6)
	v_mfma_f32_16x16x32_bf16 v[44:47], v[252:255], v[116:119], v[44:47]
	ds_read_b64 v[252:253], v185 offset:53248
	ds_read_b64 v[254:255], v185 offset:53280
	s_waitcnt lgkmcnt(6)
	v_mfma_f32_16x16x32_bf16 v[44:47], v[200:203], v[112:115], v[44:47]
	ds_read_b64 v[200:201], v185 offset:53312
	ds_read_b64 v[202:203], v185 offset:53344
	s_waitcnt lgkmcnt(6)
	v_mfma_f32_16x16x32_bf16 v[20:23], v[244:247], v[116:119], v[20:23]
	ds_read_b64 v[244:245], v185 offset:55552
	ds_read_b64 v[246:247], v185 offset:55584
	s_waitcnt lgkmcnt(6)
	v_mfma_f32_16x16x32_bf16 v[20:23], v[248:251], v[112:115], v[20:23]
	ds_read_b64 v[248:249], v185 offset:55616
	ds_read_b64 v[250:251], v185 offset:55648
	s_waitcnt lgkmcnt(6)
	v_mfma_f32_16x16x32_bf16 v[40:43], v[252:255], v[116:119], v[40:43]
	ds_read_b64 v[252:253], v185 offset:57856
	ds_read_b64 v[254:255], v185 offset:57888
	s_waitcnt lgkmcnt(6)
	v_mfma_f32_16x16x32_bf16 v[40:43], v[200:203], v[112:115], v[40:43]
	ds_read_b64 v[200:201], v185 offset:57920
	ds_read_b64 v[202:203], v185 offset:57952
	s_waitcnt lgkmcnt(6)
	v_mfma_f32_16x16x32_bf16 v[36:39], v[244:247], v[116:119], v[36:39]
	ds_read_b64 v[244:245], v185 offset:60160
	ds_read_b64 v[246:247], v185 offset:60192
	s_waitcnt lgkmcnt(6)
	v_mfma_f32_16x16x32_bf16 v[36:39], v[248:251], v[112:115], v[36:39]
	ds_read_b64 v[248:249], v185 offset:60224
	ds_read_b64 v[250:251], v185 offset:60256
	s_waitcnt lgkmcnt(6)
	v_mfma_f32_16x16x32_bf16 v[32:35], v[252:255], v[116:119], v[32:35]
	s_waitcnt lgkmcnt(4)
	v_mfma_f32_16x16x32_bf16 v[32:35], v[200:203], v[112:115], v[32:35]
	s_waitcnt lgkmcnt(2)
	v_mfma_f32_16x16x32_bf16 v[28:31], v[244:247], v[116:119], v[28:31]
	s_waitcnt lgkmcnt(0)
	v_mfma_f32_16x16x32_bf16 v[28:31], v[248:251], v[112:115], v[28:31]
	ds_write2_b32 v149, v136, v137 offset1:132
	v_add_u32_e32 v199, 0x400, v149
	ds_write2_b32 v199, v138, v139 offset0:8 offset1:140
	v_add_u32_e32 v199, 0x2000, v149
	ds_write2_b32 v199, v140, v141 offset0:64 offset1:196
	v_add_u32_e32 v199, 0x2400, v149
	ds_write2_b32 v199, v142, v143 offset0:72 offset1:204
	v_add_u32_e32 v199, 0x4200, v149
	ds_write2_b32 v199, v144, v145 offset1:132
	v_add_u32_e32 v199, 0x4600, v149
	ds_write2_b32 v199, v146, v147 offset0:8 offset1:140
	v_add_u32_e32 v199, 0x6200, v149
	ds_write2_b32 v199, v240, v241 offset0:64 offset1:196
	v_add_u32_e32 v199, 0x6600, v149
	ds_write2_b32 v199, v242, v243 offset0:72 offset1:204
	s_waitcnt lgkmcnt(0)
	s_barrier
	ds_read_b128 v[118:121], v184
	ds_read_b128 v[112:115], v184 offset:16
	ds_read_b128 v[108:111], v184 offset:32
	ds_read_b128 v[104:107], v184 offset:48
	s_waitcnt lgkmcnt(3)
	v_mov_b32_e32 v122, v119
	s_waitcnt lgkmcnt(2)
	v_mov_b32_e32 v123, v113
	v_mov_b32_e32 v116, v118
	v_mov_b32_e32 v117, v112
	v_pk_mul_f32 v[122:123], v[122:123], v[122:123]
	s_waitcnt lgkmcnt(1)
	v_mov_b32_e32 v124, v109
	v_pk_fma_f32 v[116:117], v[116:117], v[116:117], v[122:123]
	v_mov_b32_e32 v122, v120
	v_mov_b32_e32 v123, v114
	v_pk_fma_f32 v[116:117], v[122:123], v[122:123], v[116:117]
	v_mov_b32_e32 v122, v121
	v_mov_b32_e32 v123, v115
	s_waitcnt lgkmcnt(0)
	v_mov_b32_e32 v125, v105
	v_pk_fma_f32 v[116:117], v[122:123], v[122:123], v[116:117]
	v_mov_b32_e32 v122, v108
	v_mov_b32_e32 v123, v104
	v_pk_mul_f32 v[124:125], v[124:125], v[124:125]
	v_add_f32_e32 v116, v116, v117
	v_pk_fma_f32 v[122:123], v[122:123], v[122:123], v[124:125]
	v_mov_b32_e32 v124, v110
	v_mov_b32_e32 v125, v106
	v_pk_fma_f32 v[122:123], v[124:125], v[124:125], v[122:123]
	v_mov_b32_e32 v124, v111
	v_mov_b32_e32 v125, v107
	v_pk_fma_f32 v[122:123], v[124:125], v[124:125], v[122:123]
	s_nop 0
	v_add_f32_e32 v116, v116, v122
	v_add_f32_e32 v116, v116, v123
	ds_bpermute_b32 v117, v183, v116
	s_waitcnt vmcnt(7)
	v_lshlrev_b32_e32 v122, 16, v100
	v_and_b32_e32 v123, 0xffff0000, v100
	v_mul_f32_e32 v100, 0xbfb8aa3b, v122
	v_exp_f32_e32 v100, v100
	s_waitcnt lgkmcnt(0)
	v_add_f32_e32 v116, v116, v117
	ds_bpermute_b32 v117, v182, v116
	v_add_f32_e32 v100, 1.0, v100
	v_rcp_f32_e32 v124, v100
	v_mul_f32_e32 v100, 0xbfb8aa3b, v123
	s_waitcnt lgkmcnt(0)
	v_add_f32_e32 v116, v116, v117
	ds_bpermute_b32 v117, v177, v116
	v_exp_f32_e32 v100, v100
	s_waitcnt lgkmcnt(0)
	v_add_f32_e32 v116, v116, v117
	v_fmamk_f32 v116, v116, 0x3c000000, v198
	v_cmp_gt_f32_e32 vcc, s33, v116
	v_mul_f32_e32 v117, 0x4b800000, v116
	v_add_f32_e32 v100, 1.0, v100
	v_cndmask_b32_e32 v116, v116, v117, vcc
	v_rsq_f32_e32 v116, v116
	v_rcp_f32_e32 v125, v100
	v_lshlrev_b32_e32 v100, 16, v101
	v_and_b32_e32 v101, 0xffff0000, v101
	v_mul_f32_e32 v117, 0x45800000, v116
	v_cndmask_b32_e32 v116, v116, v117, vcc
	v_pk_mul_f32 v[118:119], v[118:119], v[116:117] op_sel_hi:[1,0]
	v_mul_f32_e32 v117, 0xbfb8aa3b, v100
	v_exp_f32_e32 v117, v117
	s_waitcnt vmcnt(5)
	v_pk_mul_f32 v[118:119], v[12:13], v[118:119]
	v_pk_mul_f32 v[122:123], v[124:125], v[122:123]
	v_add_f32_e32 v117, 1.0, v117
	v_pk_mul_f32 v[118:119], v[122:123], v[118:119]
	v_rcp_f32_e32 v122, v117
	v_pk_mul_f32 v[120:121], v[120:121], v[116:117] op_sel_hi:[1,0]
	v_mul_f32_e32 v117, 0xbfb8aa3b, v101
	v_exp_f32_e32 v117, v117
	v_pk_mul_f32 v[120:121], v[14:15], v[120:121]
	v_add_f32_e32 v117, 1.0, v117
	v_rcp_f32_e32 v123, v117
	v_pk_mul_f32 v[112:113], v[112:113], v[116:117] op_sel_hi:[1,0]
	v_pk_mul_f32 v[100:101], v[122:123], v[100:101]
	s_nop 0
	v_pk_mul_f32 v[100:101], v[100:101], v[120:121]
	v_lshlrev_b32_e32 v120, 16, v102
	v_and_b32_e32 v121, 0xffff0000, v102
	v_mul_f32_e32 v102, 0xbfb8aa3b, v120
	v_exp_f32_e32 v102, v102
	s_waitcnt vmcnt(4)
	v_pk_mul_f32 v[112:113], v[8:9], v[112:113]
	v_add_f32_e32 v102, 1.0, v102
	v_rcp_f32_e32 v122, v102
	v_mul_f32_e32 v102, 0xbfb8aa3b, v121
	v_exp_f32_e32 v102, v102
	s_nop 0
	v_add_f32_e32 v102, 1.0, v102
	v_rcp_f32_e32 v123, v102
	v_lshlrev_b32_e32 v102, 16, v103
	v_mul_f32_e32 v117, 0xbfb8aa3b, v102
	v_exp_f32_e32 v117, v117
	v_pk_mul_f32 v[120:121], v[122:123], v[120:121]
	v_and_b32_e32 v103, 0xffff0000, v103
	v_pk_mul_f32 v[112:113], v[120:121], v[112:113]
	v_add_f32_e32 v117, 1.0, v117
	v_rcp_f32_e32 v120, v117
	v_pk_mul_f32 v[114:115], v[114:115], v[116:117] op_sel_hi:[1,0]
	v_mul_f32_e32 v117, 0xbfb8aa3b, v103
	v_exp_f32_e32 v117, v117
	v_pk_mul_f32 v[114:115], v[10:11], v[114:115]
	v_add_f32_e32 v117, 1.0, v117
	v_rcp_f32_e32 v121, v117
	v_pk_mul_f32 v[108:109], v[108:109], v[116:117] op_sel_hi:[1,0]
	v_pk_mul_f32 v[110:111], v[110:111], v[116:117] op_sel_hi:[1,0]
	s_waitcnt vmcnt(3)
	v_pk_mul_f32 v[108:109], v[4:5], v[108:109]
	v_pk_mul_f32 v[102:103], v[120:121], v[102:103]
	v_pk_mul_f32 v[110:111], v[6:7], v[110:111]
	v_pk_mul_f32 v[102:103], v[102:103], v[114:115]
	v_lshlrev_b32_e32 v114, 16, v96
	v_and_b32_e32 v115, 0xffff0000, v96
	v_mul_f32_e32 v96, 0xbfb8aa3b, v114
	v_exp_f32_e32 v96, v96
	v_pk_mul_f32 v[104:105], v[104:105], v[116:117] op_sel_hi:[1,0]
	v_pk_mul_f32 v[106:107], v[106:107], v[116:117] op_sel_hi:[1,0]
	s_waitcnt vmcnt(2)
	v_pk_mul_f32 v[104:105], v[0:1], v[104:105]
	v_add_f32_e32 v96, 1.0, v96
	v_rcp_f32_e32 v120, v96
	v_mul_f32_e32 v96, 0xbfb8aa3b, v115
	v_exp_f32_e32 v96, v96
	v_pk_mul_f32 v[106:107], v[2:3], v[106:107]
	v_add_f32_e32 v96, 1.0, v96
	v_rcp_f32_e32 v121, v96
	v_lshlrev_b32_e32 v96, 16, v97
	v_and_b32_e32 v97, 0xffff0000, v97
	v_pk_mul_f32 v[114:115], v[120:121], v[114:115]
	s_nop 0
	v_pk_mul_f32 v[108:109], v[114:115], v[108:109]
	v_mul_f32_e32 v114, 0xbfb8aa3b, v96
	v_mul_f32_e32 v115, 0xbfb8aa3b, v97
	v_exp_f32_e32 v114, v114
	v_exp_f32_e32 v115, v115
	v_add_f32_e32 v114, 1.0, v114
	v_add_f32_e32 v115, 1.0, v115
	v_rcp_f32_e32 v114, v114
	v_rcp_f32_e32 v115, v115
	s_nop 0
	v_pk_mul_f32 v[96:97], v[114:115], v[96:97]
	s_nop 0
	v_pk_mul_f32 v[110:111], v[96:97], v[110:111]
	v_lshlrev_b32_e32 v96, 16, v98
	v_and_b32_e32 v97, 0xffff0000, v98
	v_mul_f32_e32 v98, 0xbfb8aa3b, v96
	v_exp_f32_e32 v98, v98
	s_nop 0
	v_add_f32_e32 v98, 1.0, v98
	v_rcp_f32_e32 v114, v98
	v_mul_f32_e32 v98, 0xbfb8aa3b, v97
	v_exp_f32_e32 v98, v98
	s_nop 0
	v_add_f32_e32 v98, 1.0, v98
	v_rcp_f32_e32 v115, v98
	s_nop 0
	v_pk_mul_f32 v[96:97], v[114:115], v[96:97]
	s_nop 0
	v_pk_mul_f32 v[104:105], v[96:97], v[104:105]
	v_lshlrev_b32_e32 v96, 16, v99
	v_and_b32_e32 v97, 0xffff0000, v99
	v_mul_f32_e32 v98, 0xbfb8aa3b, v96
	v_mul_f32_e32 v99, 0xbfb8aa3b, v97
	v_exp_f32_e32 v98, v98
	v_exp_f32_e32 v99, v99
	v_add_u32_e32 v114, s25, v175
	v_ashrrev_i32_e32 v115, 31, v114
	v_add_f32_e32 v98, 1.0, v98
	v_add_f32_e32 v99, 1.0, v99
	v_rcp_f32_e32 v98, v98
	v_rcp_f32_e32 v99, v99
	s_add_i32 s25, s25, 64
	s_cmpk_eq_i32 s25, 0x7c0
	v_pk_mul_f32 v[96:97], v[98:99], v[96:97]
	v_cvt_pk_bf16_f32 v99, v102, v103
	v_cvt_pk_bf16_f32 v102, v104, v105
	v_lshlrev_b64 v[104:105], 12, v[114:115]
	v_pk_mul_f32 v[106:107], v[96:97], v[106:107]
	v_cvt_pk_bf16_f32 v96, v118, v119
	v_cvt_pk_bf16_f32 v97, v100, v101
	v_cvt_pk_bf16_f32 v98, v112, v113
	v_lshl_add_u64 v[104:105], v[150:151], 0, v[104:105]
	v_cvt_pk_bf16_f32 v100, v108, v109
	v_cvt_pk_bf16_f32 v101, v110, v111
	v_cvt_pk_bf16_f32 v103, v106, v107
	global_store_dwordx4 v[104:105], v[96:99], off
	global_store_dwordx4 v[104:105], v[100:103], off offset:16
	s_cbranch_scc1 .LBB0_767
	s_waitcnt vmcnt(3)
	v_mov_b64_e32 v[102:103], v[26:27]
	s_waitcnt vmcnt(2)
	v_mov_b64_e32 v[98:99], v[18:19]
	v_mov_b64_e32 v[100:101], v[24:25]
	v_mov_b64_e32 v[96:97], v[16:17]
	s_and_saveexec_b64 s[36:37], s[4:5]
	s_cbranch_execz .LBB0_726

.LBB0_778:
	s_or_b64 exec, exec, s[4:5]
	s_waitcnt lgkmcnt(0)
	s_barrier
	v_mov_b32_e32 v204, 0x13c00
	ds_read_b32 v174, v204
	ds_read_b64 v[244:245], v187 offset:0
	ds_read_b64 v[246:247], v187 offset:32
	ds_read_b64 v[248:249], v187 offset:17408
	ds_read_b64 v[250:251], v187 offset:17440
	ds_read_b64 v[252:253], v187 offset:64
	ds_read_b64 v[254:255], v187 offset:96
	ds_read_b64 v[200:201], v187 offset:17472
	ds_read_b64 v[202:203], v187 offset:17504
	v_cvt_pk_bf16_f32 v116, v52, v53
	v_cvt_pk_bf16_f32 v117, v54, v55
	v_cvt_pk_bf16_f32 v118, v48, v49
	v_cvt_pk_bf16_f32 v119, v50, v51
	v_cvt_pk_bf16_f32 v112, v44, v45
	v_cvt_pk_bf16_f32 v113, v46, v47
	v_cvt_pk_bf16_f32 v114, v20, v21
	v_cvt_pk_bf16_f32 v115, v22, v23
	v_cvt_pk_bf16_f32 v108, v40, v41
	v_cvt_pk_bf16_f32 v109, v42, v43
	v_cvt_pk_bf16_f32 v110, v36, v37
	v_cvt_pk_bf16_f32 v111, v38, v39
	v_cvt_pk_bf16_f32 v104, v32, v33
	v_cvt_pk_bf16_f32 v105, v34, v35
	v_cvt_pk_bf16_f32 v106, v28, v29
	v_cvt_pk_bf16_f32 v107, v30, v31
	s_waitcnt lgkmcnt(6)
	v_mfma_f32_16x16x32_bf16 v[120:123], v[244:247], v[116:119], 0
	ds_read_b64 v[244:245], v187 offset:128
	ds_read_b64 v[246:247], v187 offset:160
	s_waitcnt lgkmcnt(6)
	v_mfma_f32_16x16x32_bf16 v[136:139], v[248:251], v[116:119], 0
	ds_read_b64 v[248:249], v187 offset:17536
	ds_read_b64 v[250:251], v187 offset:17568
	s_waitcnt lgkmcnt(6)
	v_mfma_f32_16x16x32_bf16 v[120:123], v[252:255], v[112:115], v[120:123]
	ds_read_b64 v[252:253], v187 offset:192
	ds_read_b64 v[254:255], v187 offset:224
	v_pk_mul_f32 v[52:53], v[52:53], v[174:175] op_sel_hi:[1,0]
	v_pk_mul_f32 v[54:55], v[54:55], v[174:175] op_sel_hi:[1,0]
	s_waitcnt lgkmcnt(6)
	v_mfma_f32_16x16x32_bf16 v[136:139], v[200:203], v[112:115], v[136:139]
	ds_read_b64 v[200:201], v187 offset:17600
	ds_read_b64 v[202:203], v187 offset:17632
	v_pk_mul_f32 v[48:49], v[48:49], v[174:175] op_sel_hi:[1,0]
	s_waitcnt lgkmcnt(6)
	v_mfma_f32_16x16x32_bf16 v[120:123], v[244:247], v[108:111], v[120:123]
	ds_read_b64 v[244:245], v187 offset:4352
	ds_read_b64 v[246:247], v187 offset:4384
	v_pk_mul_f32 v[50:51], v[50:51], v[174:175] op_sel_hi:[1,0]
	v_pk_mul_f32 v[44:45], v[44:45], v[174:175] op_sel_hi:[1,0]
	s_waitcnt lgkmcnt(6)
	v_mfma_f32_16x16x32_bf16 v[136:139], v[248:251], v[108:111], v[136:139]
	ds_read_b64 v[248:249], v187 offset:21760
	ds_read_b64 v[250:251], v187 offset:21792
	v_pk_mul_f32 v[46:47], v[46:47], v[174:175] op_sel_hi:[1,0]
	s_waitcnt lgkmcnt(6)
	v_mfma_f32_16x16x32_bf16 v[120:123], v[252:255], v[104:107], v[120:123]
	ds_read_b64 v[252:253], v187 offset:4416
	ds_read_b64 v[254:255], v187 offset:4448
	v_pk_mul_f32 v[20:21], v[20:21], v[174:175] op_sel_hi:[1,0]
	v_pk_mul_f32 v[22:23], v[22:23], v[174:175] op_sel_hi:[1,0]
	s_waitcnt lgkmcnt(6)
	v_mfma_f32_16x16x32_bf16 v[136:139], v[200:203], v[104:107], v[136:139]
	ds_read_b64 v[200:201], v187 offset:21824
	ds_read_b64 v[202:203], v187 offset:21856
	v_pk_mul_f32 v[40:41], v[40:41], v[174:175] op_sel_hi:[1,0]
	s_waitcnt lgkmcnt(6)
	v_mfma_f32_16x16x32_bf16 v[124:127], v[244:247], v[116:119], 0
	ds_read_b64 v[244:245], v187 offset:4480
	ds_read_b64 v[246:247], v187 offset:4512
	v_pk_mul_f32 v[42:43], v[42:43], v[174:175] op_sel_hi:[1,0]
	v_pk_mul_f32 v[36:37], v[36:37], v[174:175] op_sel_hi:[1,0]
	s_waitcnt lgkmcnt(6)
	v_mfma_f32_16x16x32_bf16 v[140:143], v[248:251], v[116:119], 0
	ds_read_b64 v[248:249], v187 offset:21888
	ds_read_b64 v[250:251], v187 offset:21920
	v_pk_mul_f32 v[38:39], v[38:39], v[174:175] op_sel_hi:[1,0]
	s_waitcnt lgkmcnt(6)
	v_mfma_f32_16x16x32_bf16 v[124:127], v[252:255], v[112:115], v[124:127]
	ds_read_b64 v[252:253], v187 offset:4544
	ds_read_b64 v[254:255], v187 offset:4576
	v_pk_mul_f32 v[32:33], v[32:33], v[174:175] op_sel_hi:[1,0]
	v_pk_mul_f32 v[34:35], v[34:35], v[174:175] op_sel_hi:[1,0]
	s_waitcnt lgkmcnt(6)
	v_mfma_f32_16x16x32_bf16 v[140:143], v[200:203], v[112:115], v[140:143]
	ds_read_b64 v[200:201], v187 offset:21952
	ds_read_b64 v[202:203], v187 offset:21984
	v_pk_mul_f32 v[28:29], v[28:29], v[174:175] op_sel_hi:[1,0]
	s_waitcnt lgkmcnt(6)
	v_mfma_f32_16x16x32_bf16 v[124:127], v[244:247], v[108:111], v[124:127]
	ds_read_b64 v[244:245], v187 offset:8704
	ds_read_b64 v[246:247], v187 offset:8736
	v_pk_mul_f32 v[30:31], v[30:31], v[174:175] op_sel_hi:[1,0]
	s_waitcnt lgkmcnt(6)
	v_mfma_f32_16x16x32_bf16 v[140:143], v[248:251], v[108:111], v[140:143]
	ds_read_b64 v[248:249], v187 offset:26112
	ds_read_b64 v[250:251], v187 offset:26144
	s_waitcnt lgkmcnt(6)
	v_mfma_f32_16x16x32_bf16 v[124:127], v[252:255], v[104:107], v[124:127]
	ds_read_b64 v[252:253], v187 offset:8768
	ds_read_b64 v[254:255], v187 offset:8800
	s_waitcnt lgkmcnt(6)
	v_mfma_f32_16x16x32_bf16 v[140:143], v[200:203], v[104:107], v[140:143]
	ds_read_b64 v[200:201], v187 offset:26176
	ds_read_b64 v[202:203], v187 offset:26208
	s_waitcnt lgkmcnt(6)
	v_mfma_f32_16x16x32_bf16 v[128:131], v[244:247], v[116:119], 0
	ds_read_b64 v[244:245], v187 offset:8832
	ds_read_b64 v[246:247], v187 offset:8864
	s_waitcnt lgkmcnt(6)
	v_mfma_f32_16x16x32_bf16 v[144:147], v[248:251], v[116:119], 0
	ds_read_b64 v[248:249], v187 offset:26240
	ds_read_b64 v[250:251], v187 offset:26272
	s_waitcnt lgkmcnt(6)
	v_mfma_f32_16x16x32_bf16 v[128:131], v[252:255], v[112:115], v[128:131]
	ds_read_b64 v[252:253], v187 offset:8896
	ds_read_b64 v[254:255], v187 offset:8928
	s_waitcnt lgkmcnt(6)
	v_mfma_f32_16x16x32_bf16 v[144:147], v[200:203], v[112:115], v[144:147]
	ds_read_b64 v[200:201], v187 offset:26304
	ds_read_b64 v[202:203], v187 offset:26336
	s_waitcnt lgkmcnt(6)
	v_mfma_f32_16x16x32_bf16 v[128:131], v[244:247], v[108:111], v[128:131]
	ds_read_b64 v[244:245], v187 offset:13056
	ds_read_b64 v[246:247], v187 offset:13088
	s_waitcnt lgkmcnt(6)
	v_mfma_f32_16x16x32_bf16 v[144:147], v[248:251], v[108:111], v[144:147]
	ds_read_b64 v[248:249], v187 offset:30464
	ds_read_b64 v[250:251], v187 offset:30496
	s_waitcnt lgkmcnt(6)
	v_mfma_f32_16x16x32_bf16 v[128:131], v[252:255], v[104:107], v[128:131]
	ds_read_b64 v[252:253], v187 offset:13120
	ds_read_b64 v[254:255], v187 offset:13152
	s_waitcnt lgkmcnt(6)
	v_mfma_f32_16x16x32_bf16 v[144:147], v[200:203], v[104:107], v[144:147]
	ds_read_b64 v[200:201], v187 offset:30528
	ds_read_b64 v[202:203], v187 offset:30560
	s_waitcnt lgkmcnt(6)
	v_mfma_f32_16x16x32_bf16 v[132:135], v[244:247], v[116:119], 0
	ds_read_b64 v[244:245], v187 offset:13184
	ds_read_b64 v[246:247], v187 offset:13216
	s_waitcnt lgkmcnt(6)
	v_mfma_f32_16x16x32_bf16 v[240:243], v[248:251], v[116:119], 0
	ds_read_b64 v[248:249], v187 offset:30592
	ds_read_b64 v[250:251], v187 offset:30624
	s_waitcnt lgkmcnt(6)
	v_mfma_f32_16x16x32_bf16 v[132:135], v[252:255], v[112:115], v[132:135]
	ds_read_b64 v[252:253], v187 offset:13248
	ds_read_b64 v[254:255], v187 offset:13280
	s_waitcnt lgkmcnt(6)
	v_mfma_f32_16x16x32_bf16 v[240:243], v[200:203], v[112:115], v[240:243]
	ds_read_b64 v[200:201], v187 offset:30656
	ds_read_b64 v[202:203], v187 offset:30688
	s_waitcnt lgkmcnt(6)
	v_mfma_f32_16x16x32_bf16 v[132:135], v[244:247], v[108:111], v[132:135]
	ds_read_b64 v[244:245], v186 offset:62464
	ds_read_b64 v[246:247], v186 offset:62496
	s_waitcnt lgkmcnt(6)
	v_mfma_f32_16x16x32_bf16 v[240:243], v[248:251], v[108:111], v[240:243]
	ds_read_b64 v[248:249], v186 offset:62528
	ds_read_b64 v[250:251], v186 offset:62560
	s_waitcnt lgkmcnt(6)
	v_mfma_f32_16x16x32_bf16 v[132:135], v[252:255], v[104:107], v[132:135]
	ds_read_b64 v[252:253], v185 offset:34816
	ds_read_b64 v[254:255], v185 offset:34848
	s_waitcnt lgkmcnt(6)
	v_mfma_f32_16x16x32_bf16 v[240:243], v[200:203], v[104:107], v[240:243]
	ds_read_b64 v[200:201], v185 offset:34880
	ds_read_b64 v[202:203], v185 offset:34912
	s_waitcnt lgkmcnt(6)
	v_lshlrev_b32_e32 v104, 16, v244
	v_and_b32_e32 v105, 0xffff0000, v244
	v_lshlrev_b32_e32 v106, 16, v245
	v_and_b32_e32 v107, 0xffff0000, v245
	v_pk_add_f32 v[120:121], v[104:105], v[120:121] neg_lo:[0,1] neg_hi:[0,1]
	v_pk_add_f32 v[122:123], v[106:107], v[122:123] neg_lo:[0,1] neg_hi:[0,1]
	v_lshlrev_b32_e32 v108, 16, v246
	v_and_b32_e32 v109, 0xffff0000, v246
	v_lshlrev_b32_e32 v110, 16, v247
	v_and_b32_e32 v111, 0xffff0000, v247
	v_pk_add_f32 v[124:125], v[108:109], v[124:125] neg_lo:[0,1] neg_hi:[0,1]
	v_pk_add_f32 v[126:127], v[110:111], v[126:127] neg_lo:[0,1] neg_hi:[0,1]
	ds_read_b64 v[244:245], v185 offset:37120
	ds_read_b64 v[246:247], v185 offset:37152
	v_cvt_pk_bf16_f32 v116, v120, v121
	v_cvt_pk_bf16_f32 v117, v122, v123
	v_cvt_pk_bf16_f32 v118, v124, v125
	v_cvt_pk_bf16_f32 v119, v126, v127
	s_waitcnt lgkmcnt(6)
	v_lshlrev_b32_e32 v104, 16, v248
	v_and_b32_e32 v105, 0xffff0000, v248
	v_lshlrev_b32_e32 v106, 16, v249
	v_and_b32_e32 v107, 0xffff0000, v249
	v_pk_add_f32 v[128:129], v[104:105], v[128:129] neg_lo:[0,1] neg_hi:[0,1]
	v_pk_add_f32 v[130:131], v[106:107], v[130:131] neg_lo:[0,1] neg_hi:[0,1]
	v_lshlrev_b32_e32 v108, 16, v250
	v_and_b32_e32 v109, 0xffff0000, v250
	v_lshlrev_b32_e32 v110, 16, v251
	v_and_b32_e32 v111, 0xffff0000, v251
	v_pk_add_f32 v[132:133], v[108:109], v[132:133] neg_lo:[0,1] neg_hi:[0,1]
	v_pk_add_f32 v[134:135], v[110:111], v[134:135] neg_lo:[0,1] neg_hi:[0,1]
	ds_read_b64 v[248:249], v185 offset:37184
	ds_read_b64 v[250:251], v185 offset:37216
	v_cvt_pk_bf16_f32 v112, v128, v129
	v_cvt_pk_bf16_f32 v113, v130, v131
	v_cvt_pk_bf16_f32 v114, v132, v133
	v_cvt_pk_bf16_f32 v115, v134, v135
	s_waitcnt lgkmcnt(6)
	s_nop 1
	v_mfma_f32_16x16x32_bf16 v[136:139], v[252:255], v[116:119], v[136:139]
	ds_read_b64 v[252:253], v185 offset:39424
	ds_read_b64 v[254:255], v185 offset:39456
	s_waitcnt lgkmcnt(6)
	v_mfma_f32_16x16x32_bf16 v[136:139], v[200:203], v[112:115], v[136:139]
	ds_read_b64 v[200:201], v185 offset:39488
	ds_read_b64 v[202:203], v185 offset:39520
	s_waitcnt lgkmcnt(6)
	v_mfma_f32_16x16x32_bf16 v[140:143], v[244:247], v[116:119], v[140:143]
	ds_read_b64 v[244:245], v185 offset:41728
	ds_read_b64 v[246:247], v185 offset:41760
	s_waitcnt lgkmcnt(6)
	v_mfma_f32_16x16x32_bf16 v[140:143], v[248:251], v[112:115], v[140:143]
	ds_read_b64 v[248:249], v185 offset:41792
	ds_read_b64 v[250:251], v185 offset:41824
	s_waitcnt lgkmcnt(6)
	v_mfma_f32_16x16x32_bf16 v[144:147], v[252:255], v[116:119], v[144:147]
	ds_read_b64 v[252:253], v185 offset:44032
	ds_read_b64 v[254:255], v185 offset:44064
	s_waitcnt lgkmcnt(6)
	v_mfma_f32_16x16x32_bf16 v[144:147], v[200:203], v[112:115], v[144:147]
	ds_read_b64 v[200:201], v185 offset:44096
	ds_read_b64 v[202:203], v185 offset:44128
	s_waitcnt lgkmcnt(6)
	v_mfma_f32_16x16x32_bf16 v[240:243], v[244:247], v[116:119], v[240:243]
	ds_read_b64 v[244:245], v185 offset:46336
	ds_read_b64 v[246:247], v185 offset:46368
	s_waitcnt lgkmcnt(6)
	v_mfma_f32_16x16x32_bf16 v[240:243], v[248:251], v[112:115], v[240:243]
	ds_read_b64 v[248:249], v185 offset:46400
	ds_read_b64 v[250:251], v185 offset:46432
	s_waitcnt lgkmcnt(6)
	v_mfma_f32_16x16x32_bf16 v[52:55], v[252:255], v[116:119], v[52:55]
	ds_read_b64 v[252:253], v185 offset:48640
	ds_read_b64 v[254:255], v185 offset:48672
	s_waitcnt lgkmcnt(6)
	v_mfma_f32_16x16x32_bf16 v[52:55], v[200:203], v[112:115], v[52:55]
	ds_read_b64 v[200:201], v185 offset:48704
	ds_read_b64 v[202:203], v185 offset:48736
	s_waitcnt lgkmcnt(6)
	v_mfma_f32_16x16x32_bf16 v[48:51], v[244:247], v[116:119], v[48:51]
	ds_read_b64 v[244:245], v185 offset:50944
	ds_read_b64 v[246:247], v185 offset:50976
	s_waitcnt lgkmcnt(6)
	v_mfma_f32_16x16x32_bf16 v[48:51], v[248:251], v[112:115], v[48:51]
	ds_read_b64 v[248:249], v185 offset:51008
	ds_read_b64 v[250:251], v185 offset:51040
	s_waitcnt lgkmcnt(6)
	v_mfma_f32_16x16x32_bf16 v[44:47], v[252:255], v[116:119], v[44:47]
	ds_read_b64 v[252:253], v185 offset:53248
	ds_read_b64 v[254:255], v185 offset:53280
	s_waitcnt lgkmcnt(6)
	v_mfma_f32_16x16x32_bf16 v[44:47], v[200:203], v[112:115], v[44:47]
	ds_read_b64 v[200:201], v185 offset:53312
	ds_read_b64 v[202:203], v185 offset:53344
	s_waitcnt lgkmcnt(6)
	v_mfma_f32_16x16x32_bf16 v[20:23], v[244:247], v[116:119], v[20:23]
	ds_read_b64 v[244:245], v185 offset:55552
	ds_read_b64 v[246:247], v185 offset:55584
	s_waitcnt lgkmcnt(6)
	v_mfma_f32_16x16x32_bf16 v[20:23], v[248:251], v[112:115], v[20:23]
	ds_read_b64 v[248:249], v185 offset:55616
	ds_read_b64 v[250:251], v185 offset:55648
	s_waitcnt lgkmcnt(6)
	v_mfma_f32_16x16x32_bf16 v[40:43], v[252:255], v[116:119], v[40:43]
	ds_read_b64 v[252:253], v185 offset:57856
	ds_read_b64 v[254:255], v185 offset:57888
	s_waitcnt lgkmcnt(6)
	v_mfma_f32_16x16x32_bf16 v[40:43], v[200:203], v[112:115], v[40:43]
	ds_read_b64 v[200:201], v185 offset:57920
	ds_read_b64 v[202:203], v185 offset:57952
	s_waitcnt lgkmcnt(6)
	v_mfma_f32_16x16x32_bf16 v[36:39], v[244:247], v[116:119], v[36:39]
	ds_read_b64 v[244:245], v185 offset:60160
	ds_read_b64 v[246:247], v185 offset:60192
	s_waitcnt lgkmcnt(6)
	v_mfma_f32_16x16x32_bf16 v[36:39], v[248:251], v[112:115], v[36:39]
	ds_read_b64 v[248:249], v185 offset:60224
	ds_read_b64 v[250:251], v185 offset:60256
	s_waitcnt lgkmcnt(6)
	v_mfma_f32_16x16x32_bf16 v[32:35], v[252:255], v[116:119], v[32:35]
	s_waitcnt lgkmcnt(4)
	v_mfma_f32_16x16x32_bf16 v[32:35], v[200:203], v[112:115], v[32:35]
	s_waitcnt lgkmcnt(2)
	v_mfma_f32_16x16x32_bf16 v[28:31], v[244:247], v[116:119], v[28:31]
	s_waitcnt lgkmcnt(0)
	v_mfma_f32_16x16x32_bf16 v[28:31], v[248:251], v[112:115], v[28:31]
	ds_write2_b32 v149, v136, v137 offset1:132
	v_add_u32_e32 v199, 0x400, v149
	ds_write2_b32 v199, v138, v139 offset0:8 offset1:140
	v_add_u32_e32 v199, 0x2000, v149
	ds_write2_b32 v199, v140, v141 offset0:64 offset1:196
	v_add_u32_e32 v199, 0x2400, v149
	ds_write2_b32 v199, v142, v143 offset0:72 offset1:204
	v_add_u32_e32 v199, 0x4200, v149
	ds_write2_b32 v199, v144, v145 offset1:132
	v_add_u32_e32 v199, 0x4600, v149
	ds_write2_b32 v199, v146, v147 offset0:8 offset1:140
	v_add_u32_e32 v199, 0x6200, v149
	ds_write2_b32 v199, v240, v241 offset0:64 offset1:196
	v_add_u32_e32 v199, 0x6600, v149
	ds_write2_b32 v199, v242, v243 offset0:72 offset1:204
	s_mov_b32 s4, 0x800000
	s_waitcnt lgkmcnt(0)
	s_barrier
	ds_read_b128 v[70:73], v184
	ds_read_b128 v[64:67], v184 offset:16
	ds_read_b128 v[60:63], v184 offset:32
	ds_read_b128 v[56:59], v184 offset:48
	s_waitcnt lgkmcnt(3)
	v_mov_b32_e32 v74, v71
	s_waitcnt lgkmcnt(2)
	v_mov_b32_e32 v75, v65
	v_mov_b32_e32 v68, v70
	v_mov_b32_e32 v69, v64
	v_pk_mul_f32 v[74:75], v[74:75], v[74:75]
	s_waitcnt lgkmcnt(1)
	v_mov_b32_e32 v76, v61
	v_pk_fma_f32 v[68:69], v[68:69], v[68:69], v[74:75]
	v_mov_b32_e32 v74, v72
	v_mov_b32_e32 v75, v66
	v_pk_fma_f32 v[68:69], v[74:75], v[74:75], v[68:69]
	v_mov_b32_e32 v74, v73
	v_mov_b32_e32 v75, v67
	s_waitcnt lgkmcnt(0)
	v_mov_b32_e32 v77, v57
	v_pk_fma_f32 v[68:69], v[74:75], v[74:75], v[68:69]
	v_mov_b32_e32 v74, v60
	v_mov_b32_e32 v75, v56
	v_pk_mul_f32 v[76:77], v[76:77], v[76:77]
	v_add_f32_e32 v68, v68, v69
	v_pk_fma_f32 v[74:75], v[74:75], v[74:75], v[76:77]
	v_mov_b32_e32 v76, v62
	v_mov_b32_e32 v77, v58
	v_pk_fma_f32 v[74:75], v[76:77], v[76:77], v[74:75]
	v_mov_b32_e32 v76, v63
	v_mov_b32_e32 v77, v59
	v_pk_fma_f32 v[74:75], v[76:77], v[76:77], v[74:75]
	s_nop 0
	v_add_f32_e32 v68, v68, v74
	v_add_f32_e32 v68, v68, v75
	ds_bpermute_b32 v69, v183, v68
	s_waitcnt vmcnt(3)
	v_lshlrev_b32_e32 v74, 16, v24
	v_and_b32_e32 v75, 0xffff0000, v24
	v_mul_f32_e32 v24, 0xbfb8aa3b, v74
	v_exp_f32_e32 v24, v24
	s_waitcnt lgkmcnt(0)
	v_add_f32_e32 v68, v68, v69
	ds_bpermute_b32 v69, v182, v68
	v_add_f32_e32 v24, 1.0, v24
	v_rcp_f32_e32 v76, v24
	v_mul_f32_e32 v24, 0xbfb8aa3b, v75
	s_waitcnt lgkmcnt(0)
	v_add_f32_e32 v68, v68, v69
	ds_bpermute_b32 v69, v177, v68
	v_exp_f32_e32 v24, v24
	s_waitcnt lgkmcnt(0)
	v_add_f32_e32 v68, v68, v69
	v_mov_b32_e32 v69, 0x358637bd
	v_fmac_f32_e32 v69, 0x3c000000, v68
	v_cmp_gt_f32_e32 vcc, s4, v69
	v_mul_f32_e32 v68, 0x4b800000, v69
	v_add_f32_e32 v24, 1.0, v24
	v_cndmask_b32_e32 v68, v69, v68, vcc
	v_rsq_f32_e32 v68, v68
	v_rcp_f32_e32 v77, v24
	v_lshlrev_b32_e32 v24, 16, v25
	v_and_b32_e32 v25, 0xffff0000, v25
	v_mul_f32_e32 v69, 0x45800000, v68
	v_cndmask_b32_e32 v68, v68, v69, vcc
	v_pk_mul_f32 v[70:71], v[70:71], v[68:69] op_sel_hi:[1,0]
	v_mul_f32_e32 v69, 0xbfb8aa3b, v24
	v_exp_f32_e32 v69, v69
	v_pk_mul_f32 v[12:13], v[12:13], v[70:71]
	v_pk_mul_f32 v[70:71], v[76:77], v[74:75]
	s_lshl_b64 s[4:5], s[2:3], 16
	v_add_f32_e32 v69, 1.0, v69
	v_pk_mul_f32 v[12:13], v[70:71], v[12:13]
	v_rcp_f32_e32 v70, v69
	v_pk_mul_f32 v[72:73], v[72:73], v[68:69] op_sel_hi:[1,0]
	v_mul_f32_e32 v69, 0xbfb8aa3b, v25
	v_exp_f32_e32 v69, v69
	v_pk_mul_f32 v[14:15], v[14:15], v[72:73]
	s_add_u32 s4, s28, s4
	s_addc_u32 s5, s29, s5
	v_add_f32_e32 v69, 1.0, v69
	v_rcp_f32_e32 v71, v69
	v_pk_mul_f32 v[64:65], v[64:65], v[68:69] op_sel_hi:[1,0]
	v_pk_mul_f32 v[60:61], v[60:61], v[68:69] op_sel_hi:[1,0]
	v_pk_mul_f32 v[8:9], v[8:9], v[64:65]
	v_pk_mul_f32 v[24:25], v[70:71], v[24:25]
	v_pk_mul_f32 v[64:65], v[66:67], v[68:69] op_sel_hi:[1,0]
	v_pk_mul_f32 v[14:15], v[24:25], v[14:15]
	v_lshlrev_b32_e32 v24, 16, v26
	v_and_b32_e32 v25, 0xffff0000, v26
	v_mul_f32_e32 v26, 0xbfb8aa3b, v24
	v_exp_f32_e32 v26, v26
	v_pk_mul_f32 v[10:11], v[10:11], v[64:65]
	v_pk_mul_f32 v[4:5], v[4:5], v[60:61]
	v_add_f32_e32 v26, 1.0, v26
	v_rcp_f32_e32 v70, v26
	v_mul_f32_e32 v26, 0xbfb8aa3b, v25
	v_exp_f32_e32 v26, v26
	s_nop 0
	v_add_f32_e32 v26, 1.0, v26
	v_rcp_f32_e32 v71, v26
	s_nop 0
	v_pk_mul_f32 v[24:25], v[70:71], v[24:25]
	s_nop 0
	v_pk_mul_f32 v[8:9], v[24:25], v[8:9]
	v_lshlrev_b32_e32 v24, 16, v27
	v_and_b32_e32 v25, 0xffff0000, v27
	v_mul_f32_e32 v26, 0xbfb8aa3b, v24
	v_mul_f32_e32 v27, 0xbfb8aa3b, v25
	v_exp_f32_e32 v26, v26
	v_exp_f32_e32 v27, v27
	v_add_f32_e32 v26, 1.0, v26
	v_add_f32_e32 v27, 1.0, v27
	v_rcp_f32_e32 v26, v26
	v_rcp_f32_e32 v27, v27
	s_nop 0
	v_pk_mul_f32 v[24:25], v[26:27], v[24:25]
	s_nop 0
	v_pk_mul_f32 v[10:11], v[24:25], v[10:11]
	s_waitcnt vmcnt(2)
	v_lshlrev_b32_e32 v24, 16, v16
	v_and_b32_e32 v25, 0xffff0000, v16
	v_mul_f32_e32 v16, 0xbfb8aa3b, v24
	v_exp_f32_e32 v16, v16
	s_nop 0
	v_add_f32_e32 v16, 1.0, v16
	v_rcp_f32_e32 v26, v16
	v_mul_f32_e32 v16, 0xbfb8aa3b, v25
	v_exp_f32_e32 v16, v16
	s_nop 0
	v_add_f32_e32 v16, 1.0, v16
	v_rcp_f32_e32 v27, v16
	v_lshlrev_b32_e32 v16, 16, v17
	v_and_b32_e32 v17, 0xffff0000, v17
	v_pk_mul_f32 v[24:25], v[26:27], v[24:25]
	s_nop 0
	v_pk_mul_f32 v[4:5], v[24:25], v[4:5]
	v_mul_f32_e32 v24, 0xbfb8aa3b, v16
	v_mul_f32_e32 v25, 0xbfb8aa3b, v17
	v_exp_f32_e32 v24, v24
	v_exp_f32_e32 v25, v25
	v_pk_mul_f32 v[26:27], v[62:63], v[68:69] op_sel_hi:[1,0]
	v_cvt_pk_bf16_f32 v4, v4, v5
	v_add_f32_e32 v24, 1.0, v24
	v_add_f32_e32 v25, 1.0, v25
	v_rcp_f32_e32 v24, v24
	v_rcp_f32_e32 v25, v25
	v_pk_mul_f32 v[6:7], v[6:7], v[26:27]
	v_pk_mul_f32 v[26:27], v[56:57], v[68:69] op_sel_hi:[1,0]
	v_pk_mul_f32 v[16:17], v[24:25], v[16:17]
	s_nop 0
	v_pk_mul_f32 v[6:7], v[16:17], v[6:7]
	v_lshlrev_b32_e32 v16, 16, v18
	v_and_b32_e32 v17, 0xffff0000, v18
	v_mul_f32_e32 v18, 0xbfb8aa3b, v16
	v_exp_f32_e32 v18, v18
	v_pk_mul_f32 v[0:1], v[0:1], v[26:27]
	v_cvt_pk_bf16_f32 v5, v6, v7
	v_add_f32_e32 v18, 1.0, v18
	v_rcp_f32_e32 v24, v18
	v_mul_f32_e32 v18, 0xbfb8aa3b, v17
	v_exp_f32_e32 v18, v18
	s_nop 0
	v_add_f32_e32 v18, 1.0, v18
	v_rcp_f32_e32 v25, v18
	s_nop 0
	v_pk_mul_f32 v[16:17], v[24:25], v[16:17]
	s_nop 0
	v_pk_mul_f32 v[16:17], v[16:17], v[0:1]
	v_lshlrev_b32_e32 v0, 16, v19
	v_and_b32_e32 v1, 0xffff0000, v19
	v_mul_f32_e32 v18, 0xbfb8aa3b, v0
	v_mul_f32_e32 v19, 0xbfb8aa3b, v1
	v_exp_f32_e32 v18, v18
	v_exp_f32_e32 v19, v19
	v_pk_mul_f32 v[24:25], v[58:59], v[68:69] op_sel_hi:[1,0]
	v_cvt_pk_bf16_f32 v6, v16, v17
	v_add_f32_e32 v18, 1.0, v18
	v_add_f32_e32 v19, 1.0, v19
	v_rcp_f32_e32 v18, v18
	v_rcp_f32_e32 v19, v19
	v_pk_mul_f32 v[2:3], v[2:3], v[24:25]
	v_add_u32_e32 v24, 0x7c0, v175
	v_ashrrev_i32_e32 v25, 31, v24
	v_pk_mul_f32 v[0:1], v[18:19], v[0:1]
	s_nop 0
	v_pk_mul_f32 v[18:19], v[0:1], v[2:3]
	v_cvt_pk_bf16_f32 v2, v8, v9
	v_lshlrev_b64 v[8:9], 12, v[24:25]
	v_cvt_pk_bf16_f32 v0, v12, v13
	v_cvt_pk_bf16_f32 v1, v14, v15
	v_cvt_pk_bf16_f32 v3, v10, v11
	v_lshl_add_u64 v[8:9], v[150:151], 0, v[8:9]
	v_cvt_pk_bf16_f32 v7, v18, v19
	global_store_dwordx4 v[8:9], v[0:3], off
	global_store_dwordx4 v[8:9], v[4:7], off offset:16
	s_nop 0
	v_lshlrev_b32_e32 v0, 7, v148
	v_and_b32_e32 v0, 0x1800, v0
	v_mov_b32_e32 v1, 0
	v_lshl_add_u64 v[2:3], s[4:5], 0, v[0:1]
	v_ashrrev_i32_e32 v0, 2, v148
	v_and_b32_e32 v4, -16, v0
	v_ashrrev_i32_e32 v5, 31, v4
	v_and_b32_e32 v0, 15, v148
	v_lshl_add_u64 v[2:3], v[4:5], 2, v[2:3]
	v_lshlrev_b32_e32 v0, 2, v0
	v_lshl_add_u64 v[0:1], v[2:3], 0, v[0:1]
	s_mov_b64 s[4:5], 0x4824000
	v_lshl_add_u64 v[2:3], v[0:1], 0, s[4:5]
	s_mov_b32 s4, 0x4824000
	v_add_co_u32_e32 v4, vcc, s4, v0
	s_mov_b32 s4, 0x4826000
	s_nop 0
	v_addc_co_u32_e32 v5, vcc, 0, v1, vcc
	global_store_dword v[4:5], v52, off
	global_store_dword v[2:3], v53, off offset:512
	global_store_dword v[2:3], v54, off offset:1024
	global_store_dword v[2:3], v55, off offset:1536
	v_add_co_u32_e32 v2, vcc, s4, v0
	s_mov_b32 s4, 0x4828000
	s_nop 0
	v_addc_co_u32_e32 v3, vcc, 0, v1, vcc
	global_store_dword v[2:3], v48, off
	global_store_dword v[2:3], v49, off offset:512
	global_store_dword v[2:3], v50, off offset:1024
	global_store_dword v[2:3], v51, off offset:1536
	v_add_co_u32_e32 v2, vcc, s4, v0
	s_mov_b32 s4, 0x482a000
	s_nop 0
	v_addc_co_u32_e32 v3, vcc, 0, v1, vcc
	global_store_dword v[2:3], v44, off
	global_store_dword v[2:3], v45, off offset:512
	global_store_dword v[2:3], v46, off offset:1024
	global_store_dword v[2:3], v47, off offset:1536
	v_add_co_u32_e32 v2, vcc, s4, v0
	s_mov_b32 s4, 0x482c000
	s_nop 0
	v_addc_co_u32_e32 v3, vcc, 0, v1, vcc
	global_store_dword v[2:3], v20, off
	global_store_dword v[2:3], v21, off offset:512
	global_store_dword v[2:3], v22, off offset:1024
	global_store_dword v[2:3], v23, off offset:1536
	v_add_co_u32_e32 v2, vcc, s4, v0
	s_mov_b32 s4, 0x482e000
	s_nop 0
	v_addc_co_u32_e32 v3, vcc, 0, v1, vcc
	global_store_dword v[2:3], v40, off
	global_store_dword v[2:3], v41, off offset:512
	global_store_dword v[2:3], v42, off offset:1024
	global_store_dword v[2:3], v43, off offset:1536
	v_add_co_u32_e32 v2, vcc, s4, v0
	s_mov_b32 s4, 0x4830000
	s_nop 0
	v_addc_co_u32_e32 v3, vcc, 0, v1, vcc
	global_store_dword v[2:3], v36, off
	global_store_dword v[2:3], v37, off offset:512
	global_store_dword v[2:3], v38, off offset:1024
	global_store_dword v[2:3], v39, off offset:1536
	v_add_co_u32_e32 v2, vcc, s4, v0
	s_nop 1
	v_addc_co_u32_e32 v3, vcc, 0, v1, vcc
	v_add_co_u32_e32 v0, vcc, 0x4832000, v0
	global_store_dword v[2:3], v32, off
	global_store_dword v[2:3], v33, off offset:512
	global_store_dword v[2:3], v34, off offset:1024
	global_store_dword v[2:3], v35, off offset:1536
	v_addc_co_u32_e32 v1, vcc, 0, v1, vcc
	global_store_dword v[0:1], v28, off
	global_store_dword v[0:1], v29, off offset:512
	global_store_dword v[0:1], v30, off offset:1024
	global_store_dword v[0:1], v31, off offset:1536

.LBB0_1069:
	s_or_b64 exec, exec, s[0:1]
	v_mov_b32_e32 v16, v176
	s_waitcnt lgkmcnt(0)
	s_barrier
	s_cmpk_lt_i32 s2, 0x240
	v_readfirstlane_b32 s18, v16
	s_cbranch_scc0 .LBB0_1089
	v_lshlrev_b32_e32 v0, 4, v16
	v_add_u32_e32 v1, 0x2000, v0
	v_ashrrev_i32_e32 v2, 31, v1
	v_lshrrev_b32_e32 v2, 22, v2
	v_add_u32_e32 v2, v1, v2
	v_ashrrev_i32_e32 v8, 10, v2
	v_mul_i32_i24_e32 v2, 0x400, v8
	v_sub_u32_e32 v1, v1, v2
	v_lshrrev_b32_e32 v2, 4, v1
	v_bitop3_b32 v1, v2, v1, 32 bitop3:0x6c
	v_ashrrev_i32_e32 v2, 31, v1
	v_lshrrev_b32_e32 v2, 26, v2
	v_add_u32_e32 v2, v1, v2
	v_lshlrev_b32_e32 v3, 3, v8
	v_ashrrev_i32_e32 v9, 6, v2
	v_and_b32_e32 v3, -16, v3
	v_add_u32_e32 v3, v9, v3
	v_and_b32_e32 v4, 3, v9
	s_mov_b32 s5, 0x7fffe0
	v_lshrrev_b32_e32 v5, 2, v3
	v_lshlrev_b32_e32 v6, 1, v3
	v_and_b32_e32 v2, 0xc0, v2
	v_and_or_b32 v4, v3, s5, v4
	v_and_b32_e32 v5, 4, v5
	v_and_b32_e32 v6, 24, v6
	v_sub_u32_e32 v1, v1, v2
	v_mov_b32_e32 v2, 1
	v_or3_b32 v4, v4, v5, v6
	v_lshlrev_b32_e32 v5, 5, v8
	v_ashrrev_i16_sdwa v1, v2, sext(v1) dst_sel:DWORD dst_unused:UNUSED_PAD src0_sel:DWORD src1_sel:BYTE_0
	s_movk_i32 s4, 0x1600
	v_and_b32_e32 v10, 32, v5
	v_bfe_i32 v11, v1, 0, 16
	v_mul_u32_u24_e32 v4, 0x1600, v4
	v_add_u32_e32 v1, v10, v11
	v_mul_lo_u32 v3, v3, s4
	v_add_lshl_u32 v128, v4, v1, 1
	v_add_lshl_u32 v130, v1, v3, 1
	v_bfe_i32 v1, v16, 27, 1
	v_lshrrev_b32_e32 v1, 22, v1
	v_add_u32_e32 v1, v0, v1
	v_and_b32_e32 v1, 0xfffffc00, v1
	v_sub_u32_e32 v0, v0, v1
	v_lshrrev_b32_e32 v1, 4, v0
	v_bitop3_b32 v1, v1, v0, 32 bitop3:0x6c
	v_ashrrev_i32_e32 v0, 31, v0
	v_lshrrev_b32_e32 v0, 26, v0
	v_add_u32_e32 v0, v1, v0
	v_ashrrev_i32_e32 v12, 6, v0
	v_ashrrev_i32_e32 v0, 31, v16
	v_lshrrev_b32_e32 v0, 26, v0
	v_add_u32_e32 v0, v16, v0
	v_ashrrev_i32_e32 v13, 6, v0
	v_lshlrev_b32_e32 v0, 3, v13
	v_and_b32_e32 v0, -16, v0
	v_add_u32_e32 v0, v12, v0
	v_and_b32_e32 v3, 3, v12
	v_and_or_b32 v3, v0, s5, v3
	s_ashr_i32 s1, s18, 6
	s_ashr_i32 s0, s18, 8
	s_lshl_b32 s19, s1, 10
	v_lshrrev_b32_e32 v4, 2, v0
	v_lshlrev_b32_e32 v5, 1, v0
	v_and_b32_e32 v4, 4, v4
	v_and_b32_e32 v5, 24, v5
	s_and_b32 s5, s2, 7
	s_mul_i32 s100, s5, 50
	s_add_i32 s101, s100, 48
	s_add_i32 s100, s100, -2
	s_max_i32 s100, s100, 0
	s_min_i32 s101, s101, 0x18c

	s_mul_i32 s6, s100, 0x5d2
	s_lshr_b32 s6, s6, 16
	s_mul_i32 s7, s6, 44
	s_sub_i32 s8, s100, s7
	s_add_i32 s7, s7, 44
	s_min_i32 s7, s7, s101
	s_sub_i32 s7, s7, s100
	s_cmp_eq_u32 s7, 44
	s_cselect_b32 s7, 42, s7
	s_add_i32 s100, s100, s7

	s_lshl_b32 s98, s7, 1
	s_add_i32 s98, s98, -4
	s_cmp_lg_u32 s8, 0
	s_cselect_b32 s43, 1, 0
	s_lshr_b32 s9, s2, 6
	s_lshl_b32 s6, s6, 2
	s_add_i32 s42, s6, s9
	s_bfe_u32 s44, s2, 0x30003
	s_lshl_b32 s7, s8, 8
	s_mov_b32 s8, 0
	v_or3_b32 v3, v3, v4, v5
	v_lshlrev_b32_e32 v4, 5, v13
	s_mul_i32 s9, s44, 0x2c0000
	v_and_b32_e32 v14, 32, v4
	v_mul_i32_i24_e32 v4, 64, v12
	s_ashr_i32 s10, s9, 31
	v_readlane_b32 s12, v238, 23
	v_sub_u32_e32 v1, v1, v4
	v_readlane_b32 s13, v238, 24
	s_add_u32 s9, s12, s9
	v_ashrrev_i16_sdwa v1, v2, sext(v1) dst_sel:DWORD dst_unused:UNUSED_PAD src0_sel:DWORD src1_sel:BYTE_0
	s_addc_u32 s10, s13, s10
	v_bfe_i32 v15, v1, 0, 16
	s_add_u32 s12, s9, s7
	v_mul_u32_u24_e32 v3, 0x1600, v3
	v_add_u32_e32 v1, v14, v15
	s_addc_u32 s13, s10, s8
	s_add_i32 s21, s19, 0
	v_add_lshl_u32 v132, v3, v1, 1
	s_add_i32 m0, s21, 0x10000
	s_mul_i32 s6, s42, 0x2c0000
	global_load_lds_dwordx4 v132, s[12:13]
	s_add_i32 m0, s21, 0x12000
	v_readlane_b32 s9, v239, 9
	s_mul_hi_i32 s5, s42, 0x2c0000
	s_add_u32 s6, s9, s6
	v_readlane_b32 s9, v239, 10
	s_addc_u32 s5, s9, s5
	v_mul_lo_u32 v0, v0, s4
	s_add_u32 s10, s6, s7
	v_add_lshl_u32 v134, v1, v0, 1
	global_load_lds_dwordx4 v128, s[12:13]
	s_addc_u32 s11, s5, s8
	s_mov_b32 m0, s21
	s_add_i32 s22, s21, 0x2000
	global_load_lds_dwordx4 v134, s[10:11]
	s_mov_b32 m0, s22
	s_add_u32 s6, s12, 0x160000
	global_load_lds_dwordx4 v130, s[10:11]
	s_addc_u32 s7, s13, 0
	s_add_i32 m0, s21, 0x14000
	v_mov_b32_e32 v133, 0
	global_load_lds_dwordx4 v132, s[6:7]
	s_add_i32 m0, s21, 0x16000
	v_mov_b32_e32 v129, v133
	global_load_lds_dwordx4 v128, s[6:7]
	s_add_u32 s6, s10, 0x160000
	s_addc_u32 s7, s11, 0
	s_add_i32 s23, s21, 0x4000
	s_mov_b32 m0, s23
	s_add_i32 s24, s21, 0x6000
	global_load_lds_dwordx4 v134, s[6:7]
	s_mov_b32 m0, s24
	v_mov_b32_e32 v135, v133
	global_load_lds_dwordx4 v130, s[6:7]
	v_mov_b32_e32 v131, v133
	s_movk_i32 s25, 0x2000
	s_mov_b32 s26, 0
	v_lshl_add_u64 v[6:7], s[12:13], 0, v[132:133]
	v_lshl_add_u64 v[4:5], s[12:13], 0, v[128:129]
	v_lshl_add_u64 v[2:3], s[10:11], 0, v[134:135]
	v_lshl_add_u64 v[0:1], s[10:11], 0, v[130:131]
	s_cmp_lg_u32 s0, 1
	s_mov_b32 s5, 0x16000
	s_cbranch_scc1 .LBB0_1072
	s_barrier

.LBB0_1073:
	s_and_b64 vcc, exec, s[4:5]
	s_mov_b32 s98, s99
	s_mov_b32 s43, s39
	s_mov_b32 s44, s41
	s_mov_b32 s42, s40
	s_mov_b64 s[12:13], s[8:9]
	s_mov_b64 s[10:11], s[6:7]
	global_store_dwordx4 v[154:155], v[4:7], off offset:512
	global_store_dwordx4 v[154:155], v[0:3], off offset:528
	s_cbranch_vccnz .LBB0_1086
.LBB0_1074:
	s_add_i32 s26, s26, 1
	s_cmp_lt_i32 s100, s101
	s_cbranch_scc1 .Lsk_next
	s_mov_b64 s[4:5], -1
	s_mov_b64 s[6:7], s[10:11]
	s_mov_b64 s[8:9], s[12:13]
	s_branch .LBB0_1080
.Lsk_next:
	s_mov_b64 s[4:5], 0

	s_mul_i32 s14, s100, 0x5d2
	s_lshr_b32 s14, s14, 16
	s_mul_i32 s15, s14, 44
	s_sub_i32 s16, s100, s15
	s_add_i32 s15, s15, 44
	s_min_i32 s15, s15, s101
	s_sub_i32 s15, s15, s100
	s_cmp_eq_u32 s15, 44
	s_cselect_b32 s15, 42, s15
	s_add_i32 s100, s100, s15

	s_lshl_b32 s99, s15, 1
	s_add_i32 s99, s99, -4
	s_cmp_lg_u32 s16, 0
	s_cselect_b32 s39, 1, 0
	s_lshr_b32 s17, s2, 6
	s_lshl_b32 s14, s14, 2
	s_add_i32 s40, s14, s17
	s_bfe_u32 s41, s2, 0x30003
	s_lshl_b32 s16, s16, 8
	s_mul_i32 s7, s40, 0x2c0000
	v_readlane_b32 s15, v239, 9
	s_mul_hi_i32 s6, s40, 0x2c0000
	s_add_u32 s7, s15, s7
	v_readlane_b32 s15, v239, 10
	s_addc_u32 s15, s15, s6
	s_add_u32 s6, s7, s16
	s_addc_u32 s7, s15, 0
	s_mul_i32 s9, s41, 0x2c0000
	v_readlane_b32 s14, v238, 23
	v_readlane_b32 s15, v238, 24
	s_add_u32 s9, s14, s9
	s_addc_u32 s14, s15, 0
	s_add_u32 s8, s9, s16
	s_addc_u32 s9, s14, 0

.LBB0_1081:
	ds_read_b128 v[144:147], v159
	ds_read_b128 v[148:151], v159 offset:1024
	ds_read_b128 v[152:155], v159 offset:2048
	ds_read_b128 v[162:165], v159 offset:3072
	s_add_u32 s12, s10, 0x100
	s_addc_u32 s13, s11, 0
	s_cmp_eq_u32 s47, s98
	s_cselect_b32 s17, s7, s13
	s_cselect_b32 s16, s6, s12
	s_cselect_b32 s15, s9, s46
	s_cselect_b32 s14, s8, s45
	v_lshl_add_u64 v[174:175], s[10:11], 0, v[136:137]
	s_add_i32 m0, s21, 0xc000
	ds_read_b128 v[166:169], v160
	ds_read_b128 v[170:173], v160 offset:1024
	ds_read_b128 v[182:185], v160 offset:2048
	ds_read_b128 v[186:189], v160 offset:3072
	ds_read_b128 v[190:193], v160 offset:4096
	ds_read_b128 v[194:197], v160 offset:5120
	ds_read_b128 v[198:201], v160 offset:6144
	ds_read_b128 v[202:205], v160 offset:7168
	global_load_lds_dwordx4 v[174:175], off
	v_lshl_add_u64 v[174:175], s[10:11], 0, v[138:139]
	s_add_i32 m0, s21, 0xe000
	s_nop 0
	global_load_lds_dwordx4 v[174:175], off
	s_waitcnt lgkmcnt(8)
	s_barrier
	s_waitcnt lgkmcnt(0)
	s_setprio 1
	s_waitcnt lgkmcnt(0)
	v_mfma_f32_16x16x32_bf16 v[124:127], v[144:147], v[166:169], v[124:127]
	v_mfma_f32_16x16x32_bf16 v[120:123], v[152:155], v[166:169], v[120:123]
	v_mfma_f32_16x16x32_bf16 v[112:115], v[144:147], v[182:185], v[112:115]
	v_mfma_f32_16x16x32_bf16 v[104:107], v[152:155], v[182:185], v[104:107]
	v_mfma_f32_16x16x32_bf16 v[96:99], v[144:147], v[190:193], v[96:99]
	v_mfma_f32_16x16x32_bf16 v[88:91], v[152:155], v[190:193], v[88:91]
	v_mfma_f32_16x16x32_bf16 v[80:83], v[144:147], v[198:201], v[80:83]
	v_mfma_f32_16x16x32_bf16 v[72:75], v[152:155], v[198:201], v[72:75]
	v_mfma_f32_16x16x32_bf16 v[124:127], v[148:151], v[170:173], v[124:127]
	v_mfma_f32_16x16x32_bf16 v[120:123], v[162:165], v[170:173], v[120:123]
	v_mfma_f32_16x16x32_bf16 v[112:115], v[148:151], v[186:189], v[112:115]
	v_mfma_f32_16x16x32_bf16 v[104:107], v[162:165], v[186:189], v[104:107]
	v_mfma_f32_16x16x32_bf16 v[96:99], v[148:151], v[194:197], v[96:99]
	v_mfma_f32_16x16x32_bf16 v[88:91], v[162:165], v[194:197], v[88:91]
	v_mfma_f32_16x16x32_bf16 v[80:83], v[148:151], v[202:205], v[80:83]
	v_mfma_f32_16x16x32_bf16 v[72:75], v[162:165], v[202:205], v[72:75]
	s_setprio 0
	s_barrier
	s_add_i32 s10, s37, s19
	v_lshl_add_u64 v[174:175], s[14:15], 0, v[132:133]
	s_mov_b32 m0, s10
	ds_read_b128 v[206:209], v161
	ds_read_b128 v[210:213], v161 offset:1024
	ds_read_b128 v[214:217], v161 offset:2048
	ds_read_b128 v[218:221], v161 offset:3072
	global_load_lds_dwordx4 v[174:175], off
	v_lshl_add_u64 v[222:223], s[14:15], 0, v[128:129]
	s_add_i32 m0, s10, 0x2000
	s_nop 0
	global_load_lds_dwordx4 v[222:223], off
	s_barrier
	s_waitcnt lgkmcnt(0)
	s_setprio 1
	s_waitcnt lgkmcnt(0)
	v_mfma_f32_16x16x32_bf16 v[116:119], v[206:209], v[166:169], v[116:119]
	v_mfma_f32_16x16x32_bf16 v[108:111], v[214:217], v[166:169], v[108:111]
	v_mfma_f32_16x16x32_bf16 v[100:103], v[206:209], v[182:185], v[100:103]
	v_mfma_f32_16x16x32_bf16 v[92:95], v[214:217], v[182:185], v[92:95]
	v_mfma_f32_16x16x32_bf16 v[84:87], v[206:209], v[190:193], v[84:87]
	v_mfma_f32_16x16x32_bf16 v[76:79], v[214:217], v[190:193], v[76:79]
	v_mfma_f32_16x16x32_bf16 v[68:71], v[206:209], v[198:201], v[68:71]
	v_mfma_f32_16x16x32_bf16 v[64:67], v[214:217], v[198:201], v[64:67]
	v_mfma_f32_16x16x32_bf16 v[116:119], v[210:213], v[170:173], v[116:119]
	v_mfma_f32_16x16x32_bf16 v[108:111], v[218:221], v[170:173], v[108:111]
	v_mfma_f32_16x16x32_bf16 v[100:103], v[210:213], v[186:189], v[100:103]
	v_mfma_f32_16x16x32_bf16 v[92:95], v[218:221], v[186:189], v[92:95]
	v_mfma_f32_16x16x32_bf16 v[84:87], v[210:213], v[194:197], v[84:87]
	v_mfma_f32_16x16x32_bf16 v[76:79], v[218:221], v[194:197], v[76:79]
	v_mfma_f32_16x16x32_bf16 v[68:71], v[210:213], v[202:205], v[68:71]
	v_mfma_f32_16x16x32_bf16 v[64:67], v[218:221], v[202:205], v[64:67]
	s_setprio 0
	s_mov_b32 m0, s21
	v_lshl_add_u64 v[224:225], s[16:17], 0, v[134:135]
	s_barrier
	ds_read_b128 v[166:169], v160 offset:16384
	ds_read_b128 v[170:173], v160 offset:17408
	ds_read_b128 v[182:185], v160 offset:18432
	ds_read_b128 v[186:189], v160 offset:19456
	ds_read_b128 v[190:193], v160 offset:20480
	ds_read_b128 v[194:197], v160 offset:21504
	ds_read_b128 v[198:201], v160 offset:22528
	ds_read_b128 v[202:205], v160 offset:23552
	global_load_lds_dwordx4 v[224:225], off
	v_lshl_add_u64 v[226:227], s[16:17], 0, v[130:131]
	s_mov_b32 m0, s22
	s_nop 0
	global_load_lds_dwordx4 v[226:227], off
	s_barrier
	s_waitcnt lgkmcnt(0)
	s_setprio 1
	s_waitcnt lgkmcnt(0)
	v_mfma_f32_16x16x32_bf16 v[60:63], v[144:147], v[166:169], v[60:63]
	v_mfma_f32_16x16x32_bf16 v[56:59], v[152:155], v[166:169], v[56:59]
	v_mfma_f32_16x16x32_bf16 v[48:51], v[144:147], v[182:185], v[48:51]
	v_mfma_f32_16x16x32_bf16 v[40:43], v[152:155], v[182:185], v[40:43]
	v_mfma_f32_16x16x32_bf16 v[32:35], v[144:147], v[190:193], v[32:35]
	v_mfma_f32_16x16x32_bf16 v[24:27], v[152:155], v[190:193], v[24:27]
	v_mfma_f32_16x16x32_bf16 v[16:19], v[144:147], v[198:201], v[16:19]
	v_mfma_f32_16x16x32_bf16 v[8:11], v[152:155], v[198:201], v[8:11]
	v_mfma_f32_16x16x32_bf16 v[60:63], v[148:151], v[170:173], v[60:63]
	v_mfma_f32_16x16x32_bf16 v[56:59], v[162:165], v[170:173], v[56:59]
	v_mfma_f32_16x16x32_bf16 v[48:51], v[148:151], v[186:189], v[48:51]
	v_mfma_f32_16x16x32_bf16 v[40:43], v[162:165], v[186:189], v[40:43]
	v_mfma_f32_16x16x32_bf16 v[32:35], v[148:151], v[194:197], v[32:35]
	v_mfma_f32_16x16x32_bf16 v[24:27], v[162:165], v[194:197], v[24:27]
	v_mfma_f32_16x16x32_bf16 v[16:19], v[148:151], v[202:205], v[16:19]
	v_mfma_f32_16x16x32_bf16 v[8:11], v[162:165], v[202:205], v[8:11]
	s_setprio 0
	s_barrier
	s_add_u32 s10, s14, 0x160000
	s_addc_u32 s11, s15, 0
	s_add_i32 s34, s38, s19
	v_lshl_add_u64 v[144:145], s[10:11], 0, v[132:133]
	s_mov_b32 m0, s34
	s_nop 0
	global_load_lds_dwordx4 v[144:145], off
	v_lshl_add_u64 v[144:145], s[10:11], 0, v[128:129]
	s_add_i32 m0, s34, 0x2000
	s_nop 0
	global_load_lds_dwordx4 v[144:145], off
	s_waitcnt vmcnt(6)
	s_barrier
	s_setprio 1
	v_mfma_f32_16x16x32_bf16 v[52:55], v[206:209], v[166:169], v[52:55]
	v_mfma_f32_16x16x32_bf16 v[44:47], v[214:217], v[166:169], v[44:47]
	v_mfma_f32_16x16x32_bf16 v[36:39], v[206:209], v[182:185], v[36:39]
	v_mfma_f32_16x16x32_bf16 v[28:31], v[214:217], v[182:185], v[28:31]
	v_mfma_f32_16x16x32_bf16 v[20:23], v[206:209], v[190:193], v[20:23]
	v_mfma_f32_16x16x32_bf16 v[12:15], v[214:217], v[190:193], v[12:15]
	v_mfma_f32_16x16x32_bf16 v[4:7], v[206:209], v[198:201], v[4:7]
	v_mfma_f32_16x16x32_bf16 v[0:3], v[214:217], v[198:201], v[0:3]
	v_mfma_f32_16x16x32_bf16 v[52:55], v[210:213], v[170:173], v[52:55]
	v_mfma_f32_16x16x32_bf16 v[44:47], v[218:221], v[170:173], v[44:47]
	v_mfma_f32_16x16x32_bf16 v[36:39], v[210:213], v[186:189], v[36:39]
	v_mfma_f32_16x16x32_bf16 v[28:31], v[218:221], v[186:189], v[28:31]
	v_mfma_f32_16x16x32_bf16 v[20:23], v[210:213], v[194:197], v[20:23]
	v_mfma_f32_16x16x32_bf16 v[12:15], v[218:221], v[194:197], v[12:15]
	v_mfma_f32_16x16x32_bf16 v[4:7], v[210:213], v[202:205], v[4:7]
	v_mfma_f32_16x16x32_bf16 v[0:3], v[218:221], v[202:205], v[0:3]
	s_setprio 0
	s_add_i32 s34, 0, 0x18000
	v_add_u32_e32 v162, s34, v157
	s_barrier
	ds_read_b128 v[144:147], v162
	ds_read_b128 v[148:151], v162 offset:1024
	ds_read_b128 v[152:155], v162 offset:2048
	ds_read_b128 v[162:165], v162 offset:3072
	s_add_u32 s10, s16, 0x160000
	s_addc_u32 s11, s17, 0
	s_mov_b32 m0, s23
	v_lshl_add_u64 v[206:207], s[10:11], 0, v[134:135]
	ds_read_b128 v[166:169], v160 offset:32768
	ds_read_b128 v[170:173], v160 offset:33792
	ds_read_b128 v[182:185], v160 offset:34816
	ds_read_b128 v[186:189], v160 offset:35840
	ds_read_b128 v[190:193], v160 offset:36864
	ds_read_b128 v[194:197], v160 offset:37888
	ds_read_b128 v[198:201], v160 offset:38912
	ds_read_b128 v[202:205], v160 offset:39936
	global_load_lds_dwordx4 v[206:207], off
	v_lshl_add_u64 v[206:207], s[10:11], 0, v[130:131]
	s_mov_b32 m0, s24
	s_nop 0
	global_load_lds_dwordx4 v[206:207], off
	s_waitcnt lgkmcnt(8)
	s_barrier
	s_waitcnt lgkmcnt(0)
	s_setprio 1
	s_waitcnt lgkmcnt(0)
	v_mfma_f32_16x16x32_bf16 v[124:127], v[144:147], v[166:169], v[124:127]
	v_mfma_f32_16x16x32_bf16 v[120:123], v[152:155], v[166:169], v[120:123]
	v_mfma_f32_16x16x32_bf16 v[112:115], v[144:147], v[182:185], v[112:115]
	v_mfma_f32_16x16x32_bf16 v[104:107], v[152:155], v[182:185], v[104:107]
	v_mfma_f32_16x16x32_bf16 v[96:99], v[144:147], v[190:193], v[96:99]
	v_mfma_f32_16x16x32_bf16 v[88:91], v[152:155], v[190:193], v[88:91]
	v_mfma_f32_16x16x32_bf16 v[80:83], v[144:147], v[198:201], v[80:83]
	v_mfma_f32_16x16x32_bf16 v[72:75], v[152:155], v[198:201], v[72:75]
	v_mfma_f32_16x16x32_bf16 v[124:127], v[148:151], v[170:173], v[124:127]
	v_mfma_f32_16x16x32_bf16 v[120:123], v[162:165], v[170:173], v[120:123]
	v_mfma_f32_16x16x32_bf16 v[112:115], v[148:151], v[186:189], v[112:115]
	v_mfma_f32_16x16x32_bf16 v[104:107], v[162:165], v[186:189], v[104:107]
	v_mfma_f32_16x16x32_bf16 v[96:99], v[148:151], v[194:197], v[96:99]
	v_mfma_f32_16x16x32_bf16 v[88:91], v[162:165], v[194:197], v[88:91]
	v_mfma_f32_16x16x32_bf16 v[80:83], v[148:151], v[202:205], v[80:83]
	v_mfma_f32_16x16x32_bf16 v[72:75], v[162:165], v[202:205], v[72:75]
	s_setprio 0
	s_barrier
	s_add_i32 s16, 0, 0x1c000
	s_add_i32 s10, s34, s19
	v_add_u32_e32 v177, s16, v157
	v_lshl_add_u64 v[174:175], v[174:175], 0, s[0:1]
	s_mov_b32 m0, s10
	ds_read_b128 v[206:209], v177
	ds_read_b128 v[210:213], v177 offset:1024
	ds_read_b128 v[214:217], v177 offset:2048
	ds_read_b128 v[218:221], v177 offset:3072
	global_load_lds_dwordx4 v[174:175], off
	v_lshl_add_u64 v[174:175], v[222:223], 0, s[0:1]
	s_add_i32 m0, s10, 0x2000
	s_nop 0
	global_load_lds_dwordx4 v[174:175], off
	s_barrier
	s_waitcnt lgkmcnt(0)
	s_setprio 1
	s_waitcnt lgkmcnt(0)
	v_mfma_f32_16x16x32_bf16 v[116:119], v[206:209], v[166:169], v[116:119]
	v_mfma_f32_16x16x32_bf16 v[108:111], v[214:217], v[166:169], v[108:111]
	v_mfma_f32_16x16x32_bf16 v[100:103], v[206:209], v[182:185], v[100:103]
	v_mfma_f32_16x16x32_bf16 v[92:95], v[214:217], v[182:185], v[92:95]
	v_mfma_f32_16x16x32_bf16 v[84:87], v[206:209], v[190:193], v[84:87]
	v_mfma_f32_16x16x32_bf16 v[76:79], v[214:217], v[190:193], v[76:79]
	v_mfma_f32_16x16x32_bf16 v[68:71], v[206:209], v[198:201], v[68:71]
	v_mfma_f32_16x16x32_bf16 v[64:67], v[214:217], v[198:201], v[64:67]
	v_mfma_f32_16x16x32_bf16 v[116:119], v[210:213], v[170:173], v[116:119]
	v_mfma_f32_16x16x32_bf16 v[108:111], v[218:221], v[170:173], v[108:111]
	v_mfma_f32_16x16x32_bf16 v[100:103], v[210:213], v[186:189], v[100:103]
	v_mfma_f32_16x16x32_bf16 v[92:95], v[218:221], v[186:189], v[92:95]
	v_mfma_f32_16x16x32_bf16 v[84:87], v[210:213], v[194:197], v[84:87]
	v_mfma_f32_16x16x32_bf16 v[76:79], v[218:221], v[194:197], v[76:79]
	v_mfma_f32_16x16x32_bf16 v[68:71], v[210:213], v[202:205], v[68:71]
	v_mfma_f32_16x16x32_bf16 v[64:67], v[218:221], v[202:205], v[64:67]
	s_setprio 0
	s_mov_b32 m0, s35
	v_lshl_add_u64 v[174:175], v[224:225], 0, s[0:1]
	s_barrier
	ds_read_b128 v[166:169], v160 offset:49152
	ds_read_b128 v[170:173], v160 offset:50176
	ds_read_b128 v[182:185], v160 offset:51200
	ds_read_b128 v[186:189], v160 offset:52224
	ds_read_b128 v[190:193], v160 offset:53248
	ds_read_b128 v[194:197], v160 offset:54272
	ds_read_b128 v[198:201], v160 offset:55296
	ds_read_b128 v[202:205], v160 offset:56320
	global_load_lds_dwordx4 v[174:175], off
	v_lshl_add_u64 v[174:175], v[226:227], 0, s[0:1]
	s_mov_b32 m0, s36
	s_nop 0
	global_load_lds_dwordx4 v[174:175], off
	s_barrier
	s_waitcnt lgkmcnt(0)
	s_setprio 1
	s_waitcnt lgkmcnt(0)
	v_mfma_f32_16x16x32_bf16 v[60:63], v[144:147], v[166:169], v[60:63]
	v_mfma_f32_16x16x32_bf16 v[56:59], v[152:155], v[166:169], v[56:59]
	v_mfma_f32_16x16x32_bf16 v[48:51], v[144:147], v[182:185], v[48:51]
	v_mfma_f32_16x16x32_bf16 v[40:43], v[152:155], v[182:185], v[40:43]
	v_mfma_f32_16x16x32_bf16 v[32:35], v[144:147], v[190:193], v[32:35]
	v_mfma_f32_16x16x32_bf16 v[24:27], v[152:155], v[190:193], v[24:27]
	v_mfma_f32_16x16x32_bf16 v[16:19], v[144:147], v[198:201], v[16:19]
	v_mfma_f32_16x16x32_bf16 v[8:11], v[152:155], v[198:201], v[8:11]
	v_mfma_f32_16x16x32_bf16 v[60:63], v[148:151], v[170:173], v[60:63]
	v_mfma_f32_16x16x32_bf16 v[56:59], v[162:165], v[170:173], v[56:59]
	v_mfma_f32_16x16x32_bf16 v[48:51], v[148:151], v[186:189], v[48:51]
	v_mfma_f32_16x16x32_bf16 v[40:43], v[162:165], v[186:189], v[40:43]
	v_mfma_f32_16x16x32_bf16 v[32:35], v[148:151], v[194:197], v[32:35]
	v_mfma_f32_16x16x32_bf16 v[24:27], v[162:165], v[194:197], v[24:27]
	v_mfma_f32_16x16x32_bf16 v[16:19], v[148:151], v[202:205], v[16:19]
	v_mfma_f32_16x16x32_bf16 v[8:11], v[162:165], v[202:205], v[8:11]
	s_setprio 0
	s_barrier
	s_add_u32 s10, s14, 0x160080
	s_addc_u32 s11, s15, 0
	s_add_i32 s14, s16, s19
	v_lshl_add_u64 v[144:145], s[10:11], 0, v[132:133]
	s_mov_b32 m0, s14
	s_nop 0
	global_load_lds_dwordx4 v[144:145], off
	v_lshl_add_u64 v[144:145], s[10:11], 0, v[128:129]
	s_add_i32 m0, s14, 0x2000
	s_nop 0
	global_load_lds_dwordx4 v[144:145], off
	s_waitcnt vmcnt(6)
	s_barrier
	s_setprio 1
	v_mfma_f32_16x16x32_bf16 v[52:55], v[206:209], v[166:169], v[52:55]
	v_mfma_f32_16x16x32_bf16 v[44:47], v[214:217], v[166:169], v[44:47]
	v_mfma_f32_16x16x32_bf16 v[36:39], v[206:209], v[182:185], v[36:39]
	v_mfma_f32_16x16x32_bf16 v[28:31], v[214:217], v[182:185], v[28:31]
	v_mfma_f32_16x16x32_bf16 v[20:23], v[206:209], v[190:193], v[20:23]
	v_mfma_f32_16x16x32_bf16 v[12:15], v[214:217], v[190:193], v[12:15]
	v_mfma_f32_16x16x32_bf16 v[4:7], v[206:209], v[198:201], v[4:7]
	v_mfma_f32_16x16x32_bf16 v[0:3], v[214:217], v[198:201], v[0:3]
	v_mfma_f32_16x16x32_bf16 v[52:55], v[210:213], v[170:173], v[52:55]
	v_mfma_f32_16x16x32_bf16 v[44:47], v[218:221], v[170:173], v[44:47]
	v_mfma_f32_16x16x32_bf16 v[36:39], v[210:213], v[186:189], v[36:39]
	v_mfma_f32_16x16x32_bf16 v[28:31], v[218:221], v[186:189], v[28:31]
	v_mfma_f32_16x16x32_bf16 v[20:23], v[210:213], v[194:197], v[20:23]
	v_mfma_f32_16x16x32_bf16 v[12:15], v[218:221], v[194:197], v[12:15]
	v_mfma_f32_16x16x32_bf16 v[4:7], v[210:213], v[202:205], v[4:7]
	v_mfma_f32_16x16x32_bf16 v[0:3], v[218:221], v[202:205], v[0:3]
	s_setprio 0
	s_add_i32 s47, s47, 2
	s_add_u32 s45, s45, 0x100
	s_addc_u32 s46, s46, 0
	s_cmp_gt_i32 s47, s98
	s_mov_b64 s[10:11], s[12:13]
	s_barrier
	s_cbranch_scc0 .LBB0_1081
	v_lshl_add_u32 v146, s42, 8, v156
	v_lshl_or_b32 v144, s44, 8, v158
	v_ashrrev_i32_e32 v145, 31, v144
	v_or_b32_e32 v152, 16, v146
	v_or_b32_e32 v150, 32, v146
	v_or_b32_e32 v148, 48, v146
	s_cmp_eq_u32 s43, 0
	v_ashrrev_i32_e32 v147, 31, v146
	v_lshlrev_b64 v[144:145], 2, v[144:145]
	v_ashrrev_i32_e32 v153, 31, v152
	v_ashrrev_i32_e32 v151, 31, v150
	v_ashrrev_i32_e32 v149, 31, v148
	s_cbranch_scc1 .LBB0_1084
	v_lshlrev_b64 v[154:155], 13, v[146:147]
	v_lshl_add_u64 v[154:155], s[30:31], 0, v[154:155]
	v_lshl_add_u64 v[162:163], v[154:155], 0, v[144:145]
	v_lshlrev_b64 v[154:155], 13, v[152:153]
	v_lshl_add_u64 v[154:155], s[30:31], 0, v[154:155]
	v_lshl_add_u64 v[154:155], v[154:155], 0, v[144:145]
	global_store_dwordx4 v[162:163], v[124:127], off
	global_store_dwordx4 v[162:163], v[120:123], off offset:16
	global_store_dwordx4 v[162:163], v[116:119], off offset:512
	global_store_dwordx4 v[162:163], v[108:111], off offset:528
	global_store_dwordx4 v[154:155], v[112:115], off
	global_store_dwordx4 v[154:155], v[104:107], off offset:16
	global_store_dwordx4 v[154:155], v[100:103], off offset:512
	global_store_dwordx4 v[154:155], v[92:95], off offset:528
	v_lshlrev_b64 v[154:155], 13, v[150:151]
	v_lshl_add_u64 v[154:155], s[30:31], 0, v[154:155]
	v_lshl_add_u64 v[154:155], v[154:155], 0, v[144:145]
	global_store_dwordx4 v[154:155], v[96:99], off
	global_store_dwordx4 v[154:155], v[88:91], off offset:16
	global_store_dwordx4 v[154:155], v[84:87], off offset:512
	global_store_dwordx4 v[154:155], v[76:79], off offset:528
	v_lshlrev_b64 v[154:155], 13, v[148:149]
	v_lshl_add_u64 v[154:155], s[30:31], 0, v[154:155]
	v_lshl_add_u64 v[154:155], v[154:155], 0, v[144:145]
	s_mov_b64 s[10:11], 0x100000
	global_store_dwordx4 v[154:155], v[80:83], off
	global_store_dwordx4 v[154:155], v[72:75], off offset:16
	global_store_dwordx4 v[154:155], v[68:71], off offset:512
	global_store_dwordx4 v[154:155], v[64:67], off offset:528
	v_lshl_add_u64 v[154:155], v[162:163], 0, s[10:11]
	s_mov_b32 s10, 0x100000
	v_add_co_u32_e32 v164, vcc, s10, v162
	s_mov_b64 s[10:11], 0x120000
	s_nop 0
	v_addc_co_u32_e32 v165, vcc, 0, v163, vcc
	global_store_dwordx4 v[164:165], v[60:63], off
	global_store_dwordx4 v[154:155], v[56:59], off offset:16
	global_store_dwordx4 v[154:155], v[52:55], off offset:512
	global_store_dwordx4 v[154:155], v[44:47], off offset:528
	v_lshl_add_u64 v[154:155], v[162:163], 0, s[10:11]
	s_mov_b32 s10, 0x120000
	v_add_co_u32_e32 v164, vcc, s10, v162
	s_mov_b64 s[10:11], 0x140000
	s_nop 0
	v_addc_co_u32_e32 v165, vcc, 0, v163, vcc
	global_store_dwordx4 v[164:165], v[48:51], off
	global_store_dwordx4 v[154:155], v[40:43], off offset:16
	global_store_dwordx4 v[154:155], v[36:39], off offset:512
	global_store_dwordx4 v[154:155], v[28:31], off offset:528
	v_add_co_u32_e32 v164, vcc, 0x140000, v162
	v_lshl_add_u64 v[154:155], v[162:163], 0, s[10:11]
	s_nop 0
	v_addc_co_u32_e32 v165, vcc, 0, v163, vcc
	s_mov_b64 s[10:11], 0x160000
	global_store_dwordx4 v[164:165], v[32:35], off
	global_store_dwordx4 v[154:155], v[24:27], off offset:16
	global_store_dwordx4 v[154:155], v[20:23], off offset:512
	global_store_dwordx4 v[154:155], v[12:15], off offset:528
	v_lshl_add_u64 v[154:155], v[162:163], 0, s[10:11]
	v_add_co_u32_e32 v162, vcc, 0x160000, v162
	s_nop 1
	v_addc_co_u32_e32 v163, vcc, 0, v163, vcc
	global_store_dwordx4 v[162:163], v[16:19], off
	global_store_dwordx4 v[154:155], v[8:11], off offset:16
	s_cbranch_execnz .LBB0_1073
	s_branch .LBB0_1085
